# ctx atomics fix + 60B pad after the rewritten epilogue so all later code keeps its baseline alignment mod 64
# speedup vs baseline: 1.0015x; 1.0002x over previous
; #define PG8_STAGE(bufoff, gbase, voff) do { _Pragma("unroll") for (int _i = 0; _i < 2; ++_i) \
;         __builtin_amdgcn_global_load_lds((const unsigned*)((const char*)(gbase) + (voff)[_i]), (PG8_LAS unsigned*)(lds + (bufoff) + ldsw + _i * 8192), 16, 0, 0); } while (0)
; #define PG8_LDA(dst, b, h) do { _Pragma("unroll") for (int m = 0; m < 4; ++m) _Pragma("unroll") for (int k = 0; k < 2; ++k) dst[m][k] = *(const PG8_LAS bf16x8*)(lds + PG8_SA(b, h) + aoff + m * 2048 + k * 1024); } while (0)
; #define PG8_LDB(dst, b, h) do { _Pragma("unroll") for (int n = 0; n < 2; ++n) _Pragma("unroll") for (int k = 0; k < 2; ++k) dst[n][k] = *(const PG8_LAS bf16x8*)(lds + PG8_SB(b, h) + boff + n * 2048 + k * 1024); } while (0)
; #define PG8_MMA(ai, bj, At, Bt) do { __builtin_amdgcn_s_setprio(1); _Pragma("unroll") for (int m = 0; m < 4; ++m) _Pragma("unroll") for (int n = 0; n < 2; ++n) _Pragma("unroll") for (int k = 0; k < 2; ++k) \
;         acc[ai][bj][m][n] = __builtin_amdgcn_mfma_f32_16x16x32_bf16(Bt[n][k], At[m][k], acc[ai][bj][m][n], 0, 0, 0); __builtin_amdgcn_s_setprio(0); } while (0)
; #define PG8_WAIT_L(n) asm volatile("s_waitcnt lgkmcnt(" #n ")" ::: "memory")
; #define PG8_BAR __builtin_amdgcn_s_barrier()
; #define PG8_SCHED __builtin_amdgcn_sched_barrier(0)
; template <class Epi>
; __device__ __forceinline__ void gemm_phase(PG8_LAS unsigned char* lds, const GemmD g, const Epi& E) {
;     ...
;             PG8_LDB(B0, 0, 0); PG8_SCHED; PG8_LDA(At, 0, 0); PG8_STAGE(PG8_SA(1, 1), a1 + hstepA, voffA);
;             PG8_WAIT_L(8); PG8_BAR; PG8_WAIT_L(0); PG8_MMA(0, 0, At, B0); PG8_BAR; PG8_SCHED;
;             PG8_LDB(B1, 0, 1); PG8_STAGE(PG8_SB(0, 0), b2, voffB);
;             PG8_BAR; PG8_WAIT_L(0); PG8_MMA(0, 1, At, B1); PG8_BAR;
;             PG8_LDA(At, 0, 1); PG8_STAGE(PG8_SA(0, 0), a2, voffA);
;             PG8_BAR; PG8_WAIT_L(0); PG8_MMA(1, 0, At, B0); PG8_BAR; PG8_SCHED;
.LBB0_376:
	s_add_u32 s59, s18, s58
	s_addc_u32 s60, s19, 0
	s_add_u32 s61, s59, 0x100
	s_addc_u32 s62, s60, 0
	s_and_b64 s[24:25], s[22:23], exec
	ds_read_b128 v[134:137], v158
	ds_read_b128 v[138:141], v158 offset:1024
	ds_read_b128 v[148:151], v158 offset:2048
	ds_read_b128 v[152:155], v158 offset:3072
	s_cselect_b32 s25, s13, s62
	s_cselect_b32 s24, s12, s61
	s_add_u32 s58, s16, s58
	s_addc_u32 s61, s17, 0
	s_add_u32 s58, s58, 0x100
	s_addc_u32 s61, s61, 0
	s_and_b64 s[22:23], s[22:23], exec
	s_cselect_b32 s23, s1, s61
	s_cselect_b32 s22, s0, s58
	s_add_u32 s58, s59, 0xb0080
	s_addc_u32 s59, s60, 0
	s_mov_b32 m0, s48
	v_lshl_add_u64 v[142:143], s[58:59], 0, v[144:145]
	ds_read_b128 v[164:167], v159
	ds_read_b128 v[172:175], v159 offset:1024
	ds_read_b128 v[176:179], v159 offset:2048
	ds_read_b128 v[180:183], v159 offset:3072
	ds_read_b128 v[184:187], v159 offset:4096
	ds_read_b128 v[188:191], v159 offset:5120
	ds_read_b128 v[192:195], v159 offset:6144
	ds_read_b128 v[196:199], v159 offset:7168
	global_load_lds_dwordx4 v[142:143], off
	v_lshl_add_u64 v[142:143], s[58:59], 0, v[146:147]
	s_mov_b32 m0, s49
	s_nop 0
	global_load_lds_dwordx4 v[142:143], off
	s_waitcnt lgkmcnt(8)
	s_barrier
	s_waitcnt lgkmcnt(0)
	s_setprio 1
	s_waitcnt lgkmcnt(0)
	v_mfma_f32_16x16x32_bf16 v[124:127], v[134:137], v[164:167], v[124:127]
	v_mfma_f32_16x16x32_bf16 v[92:95], v[148:151], v[164:167], v[92:95]
	v_mfma_f32_16x16x32_bf16 v[120:123], v[134:137], v[176:179], v[120:123]
	v_mfma_f32_16x16x32_bf16 v[88:91], v[148:151], v[176:179], v[88:91]
	v_mfma_f32_16x16x32_bf16 v[116:119], v[134:137], v[184:187], v[116:119]
	v_mfma_f32_16x16x32_bf16 v[84:87], v[148:151], v[184:187], v[84:87]
	v_mfma_f32_16x16x32_bf16 v[112:115], v[134:137], v[192:195], v[112:115]
	v_mfma_f32_16x16x32_bf16 v[80:83], v[148:151], v[192:195], v[80:83]
	v_mfma_f32_16x16x32_bf16 v[124:127], v[138:141], v[172:175], v[124:127]
	v_mfma_f32_16x16x32_bf16 v[92:95], v[152:155], v[172:175], v[92:95]
	v_mfma_f32_16x16x32_bf16 v[120:123], v[138:141], v[180:183], v[120:123]
	v_mfma_f32_16x16x32_bf16 v[88:91], v[152:155], v[180:183], v[88:91]
	v_mfma_f32_16x16x32_bf16 v[116:119], v[138:141], v[188:191], v[116:119]
	v_mfma_f32_16x16x32_bf16 v[84:87], v[152:155], v[188:191], v[84:87]
	v_mfma_f32_16x16x32_bf16 v[112:115], v[138:141], v[196:199], v[112:115]
	v_mfma_f32_16x16x32_bf16 v[80:83], v[152:155], v[196:199], v[80:83]
	s_setprio 0
	s_barrier
	s_mov_b32 m0, s50
	v_lshl_add_u64 v[142:143], s[22:23], 0, v[144:145]
	ds_read_b128 v[200:203], v160
	ds_read_b128 v[204:207], v160 offset:1024
	ds_read_b128 v[208:211], v160 offset:2048
	ds_read_b128 v[212:215], v160 offset:3072
	global_load_lds_dwordx4 v[142:143], off
	v_lshl_add_u64 v[216:217], s[22:23], 0, v[146:147]
	s_mov_b32 m0, s51
	s_nop 0
	global_load_lds_dwordx4 v[216:217], off
	s_barrier
	s_waitcnt lgkmcnt(0)
	s_setprio 1
	s_waitcnt lgkmcnt(0)
	v_mfma_f32_16x16x32_bf16 v[60:63], v[200:203], v[164:167], v[60:63]
	v_mfma_f32_16x16x32_bf16 v[40:43], v[208:211], v[164:167], v[40:43]
	v_mfma_f32_16x16x32_bf16 v[56:59], v[200:203], v[176:179], v[56:59]
	v_mfma_f32_16x16x32_bf16 v[32:35], v[208:211], v[176:179], v[32:35]
	v_mfma_f32_16x16x32_bf16 v[52:55], v[200:203], v[184:187], v[52:55]
	v_mfma_f32_16x16x32_bf16 v[24:27], v[208:211], v[184:187], v[24:27]
	v_mfma_f32_16x16x32_bf16 v[48:51], v[200:203], v[192:195], v[48:51]
	v_mfma_f32_16x16x32_bf16 v[16:19], v[208:211], v[192:195], v[16:19]
	v_mfma_f32_16x16x32_bf16 v[60:63], v[204:207], v[172:175], v[60:63]
	v_mfma_f32_16x16x32_bf16 v[40:43], v[212:215], v[172:175], v[40:43]
	v_mfma_f32_16x16x32_bf16 v[56:59], v[204:207], v[180:183], v[56:59]
	v_mfma_f32_16x16x32_bf16 v[32:35], v[212:215], v[180:183], v[32:35]
	v_mfma_f32_16x16x32_bf16 v[52:55], v[204:207], v[188:191], v[52:55]
	v_mfma_f32_16x16x32_bf16 v[24:27], v[212:215], v[188:191], v[24:27]
	v_mfma_f32_16x16x32_bf16 v[48:51], v[204:207], v[196:199], v[48:51]
	v_mfma_f32_16x16x32_bf16 v[16:19], v[212:215], v[196:199], v[16:19]
	s_setprio 0
	s_mov_b32 m0, s34
	v_lshl_add_u64 v[218:219], s[24:25], 0, v[144:145]
	s_barrier
	ds_read_b128 v[164:167], v159 offset:16384
	ds_read_b128 v[172:175], v159 offset:17408
	ds_read_b128 v[176:179], v159 offset:18432
	ds_read_b128 v[180:183], v159 offset:19456
	ds_read_b128 v[184:187], v159 offset:20480
	ds_read_b128 v[188:191], v159 offset:21504
	ds_read_b128 v[192:195], v159 offset:22528
	ds_read_b128 v[196:199], v159 offset:23552
	global_load_lds_dwordx4 v[218:219], off
	v_lshl_add_u64 v[220:221], s[24:25], 0, v[146:147]
	s_mov_b32 m0, s35
	s_nop 0
	global_load_lds_dwordx4 v[220:221], off
	s_barrier
	s_waitcnt lgkmcnt(0)
	s_setprio 1
	s_waitcnt lgkmcnt(0)
	v_mfma_f32_16x16x32_bf16 v[108:111], v[134:137], v[164:167], v[108:111]
	v_mfma_f32_16x16x32_bf16 v[76:79], v[148:151], v[164:167], v[76:79]
	v_mfma_f32_16x16x32_bf16 v[104:107], v[134:137], v[176:179], v[104:107]
	v_mfma_f32_16x16x32_bf16 v[72:75], v[148:151], v[176:179], v[72:75]
	v_mfma_f32_16x16x32_bf16 v[100:103], v[134:137], v[184:187], v[100:103]
	v_mfma_f32_16x16x32_bf16 v[68:71], v[148:151], v[184:187], v[68:71]
	v_mfma_f32_16x16x32_bf16 v[96:99], v[134:137], v[192:195], v[96:99]
	v_mfma_f32_16x16x32_bf16 v[64:67], v[148:151], v[192:195], v[64:67]
	v_mfma_f32_16x16x32_bf16 v[108:111], v[138:141], v[172:175], v[108:111]
	v_mfma_f32_16x16x32_bf16 v[76:79], v[152:155], v[172:175], v[76:79]
	v_mfma_f32_16x16x32_bf16 v[104:107], v[138:141], v[180:183], v[104:107]
	v_mfma_f32_16x16x32_bf16 v[72:75], v[152:155], v[180:183], v[72:75]
	v_mfma_f32_16x16x32_bf16 v[100:103], v[138:141], v[188:191], v[100:103]
	v_mfma_f32_16x16x32_bf16 v[68:71], v[152:155], v[188:191], v[68:71]
	v_mfma_f32_16x16x32_bf16 v[96:99], v[138:141], v[196:199], v[96:99]
	v_mfma_f32_16x16x32_bf16 v[64:67], v[152:155], v[196:199], v[64:67]
	s_setprio 0
	s_barrier
; #define PG8_STAGE(bufoff, gbase, voff) do { _Pragma("unroll") for (int _i = 0; _i < 2; ++_i) \
;         __builtin_amdgcn_global_load_lds((const unsigned*)((const char*)(gbase) + (voff)[_i]), (PG8_LAS unsigned*)(lds + (bufoff) + ldsw + _i * 8192), 16, 0, 0); } while (0)
; #define PG8_LDA(dst, b, h) do { _Pragma("unroll") for (int m = 0; m < 4; ++m) _Pragma("unroll") for (int k = 0; k < 2; ++k) dst[m][k] = *(const PG8_LAS bf16x8*)(lds + PG8_SA(b, h) + aoff + m * 2048 + k * 1024); } while (0)
; #define PG8_LDB(dst, b, h) do { _Pragma("unroll") for (int n = 0; n < 2; ++n) _Pragma("unroll") for (int k = 0; k < 2; ++k) dst[n][k] = *(const PG8_LAS bf16x8*)(lds + PG8_SB(b, h) + boff + n * 2048 + k * 1024); } while (0)
; #define PG8_MMA(ai, bj, At, Bt) do { __builtin_amdgcn_s_setprio(1); _Pragma("unroll") for (int m = 0; m < 4; ++m) _Pragma("unroll") for (int n = 0; n < 2; ++n) _Pragma("unroll") for (int k = 0; k < 2; ++k) \
;         acc[ai][bj][m][n] = __builtin_amdgcn_mfma_f32_16x16x32_bf16(Bt[n][k], At[m][k], acc[ai][bj][m][n], 0, 0, 0); __builtin_amdgcn_s_setprio(0); } while (0)
; #define PG8_WAIT_V(n) asm volatile("s_waitcnt vmcnt(" #n ")" ::: "memory")
; #define PG8_WAIT_L(n) asm volatile("s_waitcnt lgkmcnt(" #n ")" ::: "memory")
; #define PG8_BAR __builtin_amdgcn_s_barrier()
; #define PG8_SCHED __builtin_amdgcn_sched_barrier(0)
; template <class Epi>
; __device__ __forceinline__ void gemm_phase(PG8_LAS unsigned char* lds, const GemmD g, const Epi& E) {
;     ...
;             PG8_STAGE(PG8_SB(0, 1), b2 + hstepB, voffB);
;             PG8_WAIT_V(6); PG8_BAR; PG8_MMA(1, 1, At, B1); PG8_BAR;
;             PG8_LDB(B0, 1, 0); PG8_SCHED; PG8_LDA(At, 1, 0); PG8_STAGE(PG8_SA(0, 1), a2 + hstepA, voffA);
;             PG8_WAIT_L(8); PG8_BAR; PG8_WAIT_L(0); PG8_MMA(0, 0, At, B0); PG8_BAR; PG8_SCHED;
;             PG8_LDB(B1, 1, 1); PG8_STAGE(PG8_SB(1, 0), b3, voffB);
;             PG8_BAR; PG8_WAIT_L(0); PG8_MMA(0, 1, At, B1); PG8_BAR;
;             PG8_LDA(At, 1, 1); PG8_STAGE(PG8_SA(1, 0), a3, voffA);
;             PG8_BAR; PG8_WAIT_L(0); PG8_MMA(1, 0, At, B0); PG8_BAR; PG8_SCHED;
	s_add_u32 s58, s22, 0xb0000
	s_addc_u32 s59, s23, 0
	s_mov_b32 m0, s52
	v_lshl_add_u64 v[134:135], s[58:59], 0, v[144:145]
	global_load_lds_dwordx4 v[134:135], off
	v_lshl_add_u64 v[134:135], s[58:59], 0, v[146:147]
	s_mov_b32 m0, s53
	s_nop 0
	global_load_lds_dwordx4 v[134:135], off
	s_waitcnt vmcnt(6)
	s_barrier
	s_setprio 1
	v_mfma_f32_16x16x32_bf16 v[44:47], v[200:203], v[164:167], v[44:47]
	v_mfma_f32_16x16x32_bf16 v[12:15], v[208:211], v[164:167], v[12:15]
	v_mfma_f32_16x16x32_bf16 v[36:39], v[200:203], v[176:179], v[36:39]
	v_mfma_f32_16x16x32_bf16 v[8:11], v[208:211], v[176:179], v[8:11]
	v_mfma_f32_16x16x32_bf16 v[28:31], v[200:203], v[184:187], v[28:31]
	v_mfma_f32_16x16x32_bf16 v[4:7], v[208:211], v[184:187], v[4:7]
	v_mfma_f32_16x16x32_bf16 v[20:23], v[200:203], v[192:195], v[20:23]
	v_mfma_f32_16x16x32_bf16 v[0:3], v[208:211], v[192:195], v[0:3]
	v_mfma_f32_16x16x32_bf16 v[44:47], v[204:207], v[172:175], v[44:47]
	v_mfma_f32_16x16x32_bf16 v[12:15], v[212:215], v[172:175], v[12:15]
	v_mfma_f32_16x16x32_bf16 v[36:39], v[204:207], v[180:183], v[36:39]
	v_mfma_f32_16x16x32_bf16 v[8:11], v[212:215], v[180:183], v[8:11]
	v_mfma_f32_16x16x32_bf16 v[28:31], v[204:207], v[188:191], v[28:31]
	v_mfma_f32_16x16x32_bf16 v[4:7], v[212:215], v[188:191], v[4:7]
	v_mfma_f32_16x16x32_bf16 v[20:23], v[204:207], v[196:199], v[20:23]
	v_mfma_f32_16x16x32_bf16 v[0:3], v[212:215], v[196:199], v[0:3]
	s_setprio 0
	s_barrier
	ds_read_b128 v[134:137], v161
	ds_read_b128 v[138:141], v161 offset:1024
	ds_read_b128 v[148:151], v161 offset:2048
	ds_read_b128 v[152:155], v161 offset:3072
	s_add_u32 s24, s24, 0xb0000
	s_addc_u32 s25, s25, 0
	s_mov_b32 m0, s36
	v_lshl_add_u64 v[200:201], s[24:25], 0, v[144:145]
	ds_read_b128 v[164:167], v159 offset:32768
	ds_read_b128 v[172:175], v159 offset:33792
	ds_read_b128 v[176:179], v159 offset:34816
	ds_read_b128 v[180:183], v159 offset:35840
	ds_read_b128 v[184:187], v159 offset:36864
	ds_read_b128 v[188:191], v159 offset:37888
	ds_read_b128 v[192:195], v159 offset:38912
	ds_read_b128 v[196:199], v159 offset:39936
	global_load_lds_dwordx4 v[200:201], off
	v_lshl_add_u64 v[200:201], s[24:25], 0, v[146:147]
	s_mov_b32 m0, s37
	s_nop 0
	global_load_lds_dwordx4 v[200:201], off
	s_waitcnt lgkmcnt(8)
	s_barrier
	s_waitcnt lgkmcnt(0)
	s_setprio 1
	s_waitcnt lgkmcnt(0)
	v_mfma_f32_16x16x32_bf16 v[124:127], v[134:137], v[164:167], v[124:127]
	v_mfma_f32_16x16x32_bf16 v[92:95], v[148:151], v[164:167], v[92:95]
	v_mfma_f32_16x16x32_bf16 v[120:123], v[134:137], v[176:179], v[120:123]
	v_mfma_f32_16x16x32_bf16 v[88:91], v[148:151], v[176:179], v[88:91]
	v_mfma_f32_16x16x32_bf16 v[116:119], v[134:137], v[184:187], v[116:119]
	v_mfma_f32_16x16x32_bf16 v[84:87], v[148:151], v[184:187], v[84:87]
	v_mfma_f32_16x16x32_bf16 v[112:115], v[134:137], v[192:195], v[112:115]
	v_mfma_f32_16x16x32_bf16 v[80:83], v[148:151], v[192:195], v[80:83]
	v_mfma_f32_16x16x32_bf16 v[124:127], v[138:141], v[172:175], v[124:127]
	v_mfma_f32_16x16x32_bf16 v[92:95], v[152:155], v[172:175], v[92:95]
	v_mfma_f32_16x16x32_bf16 v[120:123], v[138:141], v[180:183], v[120:123]
	v_mfma_f32_16x16x32_bf16 v[88:91], v[152:155], v[180:183], v[88:91]
	v_mfma_f32_16x16x32_bf16 v[116:119], v[138:141], v[188:191], v[116:119]
	v_mfma_f32_16x16x32_bf16 v[84:87], v[152:155], v[188:191], v[84:87]
	v_mfma_f32_16x16x32_bf16 v[112:115], v[138:141], v[196:199], v[112:115]
	v_mfma_f32_16x16x32_bf16 v[80:83], v[152:155], v[196:199], v[80:83]
	s_setprio 0
	s_barrier
	s_mov_b32 m0, s55
	v_lshl_add_u64 v[142:143], v[142:143], 0, s[6:7]
	ds_read_b128 v[200:203], v162
	ds_read_b128 v[204:207], v162 offset:1024
	ds_read_b128 v[208:211], v162 offset:2048
	ds_read_b128 v[212:215], v162 offset:3072
	global_load_lds_dwordx4 v[142:143], off
	v_lshl_add_u64 v[142:143], v[216:217], 0, s[6:7]
	s_add_i32 m0, s55, 0x2000
	s_nop 0
	global_load_lds_dwordx4 v[142:143], off
	s_barrier
	s_waitcnt lgkmcnt(0)
	s_setprio 1
	s_waitcnt lgkmcnt(0)
	v_mfma_f32_16x16x32_bf16 v[60:63], v[200:203], v[164:167], v[60:63]
	v_mfma_f32_16x16x32_bf16 v[40:43], v[208:211], v[164:167], v[40:43]
	v_mfma_f32_16x16x32_bf16 v[56:59], v[200:203], v[176:179], v[56:59]
	v_mfma_f32_16x16x32_bf16 v[32:35], v[208:211], v[176:179], v[32:35]
	v_mfma_f32_16x16x32_bf16 v[52:55], v[200:203], v[184:187], v[52:55]
	v_mfma_f32_16x16x32_bf16 v[24:27], v[208:211], v[184:187], v[24:27]
	v_mfma_f32_16x16x32_bf16 v[48:51], v[200:203], v[192:195], v[48:51]
	v_mfma_f32_16x16x32_bf16 v[16:19], v[208:211], v[192:195], v[16:19]
	v_mfma_f32_16x16x32_bf16 v[60:63], v[204:207], v[172:175], v[60:63]
	v_mfma_f32_16x16x32_bf16 v[40:43], v[212:215], v[172:175], v[40:43]
	v_mfma_f32_16x16x32_bf16 v[56:59], v[204:207], v[180:183], v[56:59]
	v_mfma_f32_16x16x32_bf16 v[32:35], v[212:215], v[180:183], v[32:35]
	v_mfma_f32_16x16x32_bf16 v[52:55], v[204:207], v[188:191], v[52:55]
	v_mfma_f32_16x16x32_bf16 v[24:27], v[212:215], v[188:191], v[24:27]
	v_mfma_f32_16x16x32_bf16 v[48:51], v[204:207], v[196:199], v[48:51]
	v_mfma_f32_16x16x32_bf16 v[16:19], v[212:215], v[196:199], v[16:19]
	s_setprio 0
	s_mov_b32 m0, s40
	v_lshl_add_u64 v[142:143], v[218:219], 0, s[6:7]
	s_barrier
	ds_read_b128 v[164:167], v159 offset:49152
	ds_read_b128 v[172:175], v159 offset:50176
	ds_read_b128 v[176:179], v159 offset:51200
	ds_read_b128 v[180:183], v159 offset:52224
	ds_read_b128 v[184:187], v159 offset:53248
	ds_read_b128 v[188:191], v159 offset:54272
	ds_read_b128 v[192:195], v159 offset:55296
	ds_read_b128 v[196:199], v159 offset:56320
	global_load_lds_dwordx4 v[142:143], off
	v_lshl_add_u64 v[142:143], v[220:221], 0, s[6:7]
	s_mov_b32 m0, s41
	s_nop 0
	global_load_lds_dwordx4 v[142:143], off
	s_barrier
; #define PG8_STAGE(bufoff, gbase, voff) do { _Pragma("unroll") for (int _i = 0; _i < 2; ++_i) \
;         __builtin_amdgcn_global_load_lds((const unsigned*)((const char*)(gbase) + (voff)[_i]), (PG8_LAS unsigned*)(lds + (bufoff) + ldsw + _i * 8192), 16, 0, 0); } while (0)
; #define PG8_MMA(ai, bj, At, Bt) do { __builtin_amdgcn_s_setprio(1); _Pragma("unroll") for (int m = 0; m < 4; ++m) _Pragma("unroll") for (int n = 0; n < 2; ++n) _Pragma("unroll") for (int k = 0; k < 2; ++k) \
;         acc[ai][bj][m][n] = __builtin_amdgcn_mfma_f32_16x16x32_bf16(Bt[n][k], At[m][k], acc[ai][bj][m][n], 0, 0, 0); __builtin_amdgcn_s_setprio(0); } while (0)
; #define PG8_WAIT_V(n) asm volatile("s_waitcnt vmcnt(" #n ")" ::: "memory")
; #define PG8_WAIT_L(n) asm volatile("s_waitcnt lgkmcnt(" #n ")" ::: "memory")
; #define PG8_BAR __builtin_amdgcn_s_barrier()
; #define PG8_SCHED __builtin_amdgcn_sched_barrier(0)
; template <class Epi>
; __device__ __forceinline__ void gemm_phase(PG8_LAS unsigned char* lds, const GemmD g, const Epi& E) {
;     ...
;             PG8_BAR; PG8_WAIT_L(0); PG8_MMA(1, 0, At, B0); PG8_BAR; PG8_SCHED;
;             PG8_STAGE(PG8_SB(1, 1), b3 + hstepB, voffB);
;             PG8_WAIT_V(6); PG8_BAR; PG8_MMA(1, 1, At, B1); PG8_BAR;
;     __device__ __forceinline__ void operator()(const AccT& acc, const Unit& u, int wr, int wc, int fr, int fq) const {
; #pragma unroll
;         for (int bj = 0; bj < 2; ++bj)
; #pragma unroll
;             for (int nn = 0; nn < 2; ++nn) {
;                 const int n = 256 * u.pn + 128 * bj + 32 * wc + 16 * nn + 4 * fq;
;                 const f32x4 gt = *(const f32x4*)(mod + 4 * 9216 + 2 * 1024 + n) * 0.5f;
;                 float* xb = XR + (size_t)(256 * u.pm + 64 * wr + fr) * 1024 + n;
	s_waitcnt lgkmcnt(0)
	s_setprio 1
	s_waitcnt lgkmcnt(0)
	v_mfma_f32_16x16x32_bf16 v[108:111], v[134:137], v[164:167], v[108:111]
	v_mfma_f32_16x16x32_bf16 v[76:79], v[148:151], v[164:167], v[76:79]
	v_mfma_f32_16x16x32_bf16 v[104:107], v[134:137], v[176:179], v[104:107]
	v_mfma_f32_16x16x32_bf16 v[72:75], v[148:151], v[176:179], v[72:75]
	v_mfma_f32_16x16x32_bf16 v[100:103], v[134:137], v[184:187], v[100:103]
	v_mfma_f32_16x16x32_bf16 v[68:71], v[148:151], v[184:187], v[68:71]
	v_mfma_f32_16x16x32_bf16 v[96:99], v[134:137], v[192:195], v[96:99]
	v_mfma_f32_16x16x32_bf16 v[64:67], v[148:151], v[192:195], v[64:67]
	v_mfma_f32_16x16x32_bf16 v[108:111], v[138:141], v[172:175], v[108:111]
	v_mfma_f32_16x16x32_bf16 v[76:79], v[152:155], v[172:175], v[76:79]
	v_mfma_f32_16x16x32_bf16 v[104:107], v[138:141], v[180:183], v[104:107]
	v_mfma_f32_16x16x32_bf16 v[72:75], v[152:155], v[180:183], v[72:75]
	v_mfma_f32_16x16x32_bf16 v[100:103], v[138:141], v[188:191], v[100:103]
	v_mfma_f32_16x16x32_bf16 v[68:71], v[152:155], v[188:191], v[68:71]
	v_mfma_f32_16x16x32_bf16 v[96:99], v[138:141], v[196:199], v[96:99]
	v_mfma_f32_16x16x32_bf16 v[64:67], v[152:155], v[196:199], v[64:67]
	s_setprio 0
	s_barrier
	s_add_u32 s22, s22, 0xb0080
	s_addc_u32 s23, s23, 0
	s_add_i32 s24, s54, s31
	v_lshl_add_u64 v[134:135], s[22:23], 0, v[144:145]
	s_mov_b32 m0, s24
	s_nop 0
	global_load_lds_dwordx4 v[134:135], off
	v_lshl_add_u64 v[134:135], s[22:23], 0, v[146:147]
	s_add_i32 m0, s24, 0x2000
	s_nop 0
	global_load_lds_dwordx4 v[134:135], off
	s_waitcnt vmcnt(6)
	s_barrier
	s_setprio 1
	v_mfma_f32_16x16x32_bf16 v[44:47], v[200:203], v[164:167], v[44:47]
	v_mfma_f32_16x16x32_bf16 v[12:15], v[208:211], v[164:167], v[12:15]
	v_mfma_f32_16x16x32_bf16 v[36:39], v[200:203], v[176:179], v[36:39]
	v_mfma_f32_16x16x32_bf16 v[8:11], v[208:211], v[176:179], v[8:11]
	v_mfma_f32_16x16x32_bf16 v[28:31], v[200:203], v[184:187], v[28:31]
	v_mfma_f32_16x16x32_bf16 v[4:7], v[208:211], v[184:187], v[4:7]
	v_mfma_f32_16x16x32_bf16 v[20:23], v[200:203], v[192:195], v[20:23]
	v_mfma_f32_16x16x32_bf16 v[0:3], v[208:211], v[192:195], v[0:3]
	v_mfma_f32_16x16x32_bf16 v[44:47], v[204:207], v[172:175], v[44:47]
	v_mfma_f32_16x16x32_bf16 v[12:15], v[212:215], v[172:175], v[12:15]
	v_mfma_f32_16x16x32_bf16 v[36:39], v[204:207], v[180:183], v[36:39]
	v_mfma_f32_16x16x32_bf16 v[8:11], v[212:215], v[180:183], v[8:11]
	v_mfma_f32_16x16x32_bf16 v[28:31], v[204:207], v[188:191], v[28:31]
	v_mfma_f32_16x16x32_bf16 v[4:7], v[212:215], v[188:191], v[4:7]
	v_mfma_f32_16x16x32_bf16 v[20:23], v[204:207], v[196:199], v[20:23]
	v_mfma_f32_16x16x32_bf16 v[0:3], v[212:215], v[196:199], v[0:3]
	s_setprio 0
	s_movk_i32 s58, 0x100
	s_and_b64 vcc, exec, s[20:21]
	s_mov_b64 s[22:23], -1
	s_mov_b64 s[20:21], 0
	s_barrier
	s_cbranch_vccnz .LBB0_376
	v_lshl_add_u32 v128, s56, 8, v156
	v_lshl_or_b32 v154, s57, 8, v157
	v_mov_b32_e32 v155, v129
	s_and_b32 s57, s14, 3
	s_mov_b32 s56, s15
	v_and_or_b32 v154, v128, 3, v154
	v_and_or_b32 v128, v128, -4, 1
	s_mov_b64 s[16:17], s[0:1]
	s_mov_b64 s[18:19], s[12:13]
	v_lshlrev_b64 v[134:135], 2, v[154:155]
	v_lshl_add_u64 v[136:137], s[10:11], 0, v[134:135]
	global_load_dword v163, v[136:137], off
	global_load_dword v164, v[136:137], off offset:64
	global_load_dword v165, v[136:137], off offset:512
	global_load_dword v166, v[136:137], off offset:576
	v_lshlrev_b64 v[136:137], 12, v[128:129]
	v_lshl_add_u64 v[136:137], s[4:5], 0, v[136:137]
	v_lshl_add_u64 v[152:153], v[136:137], 0, v[134:135]
	v_add_co_u32_e32 v150, vcc, s39, v152
	s_nop 1
	v_addc_co_u32_e32 v151, vcc, 0, v153, vcc
	v_add_co_u32_e32 v148, vcc, s42, v152
	s_nop 1
	v_addc_co_u32_e32 v149, vcc, 0, v153, vcc
	v_add_co_u32_e32 v142, vcc, s43, v152
	s_nop 1
	v_addc_co_u32_e32 v143, vcc, 0, v153, vcc
	v_add_co_u32_e32 v140, vcc, s44, v152
	s_nop 1
	v_addc_co_u32_e32 v141, vcc, 0, v153, vcc
	v_add_co_u32_e32 v138, vcc, s45, v152
	s_nop 1
	v_addc_co_u32_e32 v139, vcc, 0, v153, vcc
	v_add_co_u32_e32 v136, vcc, s46, v152
	s_nop 1
	v_addc_co_u32_e32 v137, vcc, 0, v153, vcc
	v_add_co_u32_e32 v134, vcc, s47, v152
	s_nop 1
	v_addc_co_u32_e32 v135, vcc, 0, v153, vcc
	s_mov_b32 s98, 0x2000
	s_mov_b32 s99, 0
	s_mov_b32 s100, 0xffffe000
	s_mov_b32 s101, -1
	s_waitcnt vmcnt(0)
;     __device__ __forceinline__ void operator()(const AccT& acc, const Unit& u, int wr, int wc, int fr, int fq) const {
;     ...
;                 const int n = 256 * u.pn + 128 * bj + 32 * wc + 16 * nn + 4 * fq;
;                 const f32x4 gt = *(const f32x4*)(mod + 4 * 9216 + 2 * 1024 + n) * 0.5f;
;                 float* xb = XR + (size_t)(256 * u.pm + 64 * wr + fr) * 1024 + n;
; #pragma unroll
;                 for (int ai = 0; ai < 2; ++ai)
; #pragma unroll
;                     for (int mm = 0; mm < 4; ++mm) {
;                         float* xp = xb + (size_t)(128 * ai + 16 * mm) * 1024;
;                         const f32x4 v = acc[ai][bj][mm][nn] * gt;
; #pragma unroll
;                         for (int r = 0; r < 4; ++r) (void)__hip_atomic_fetch_add(xp + r, v[r], __ATOMIC_RELAXED, __HIP_MEMORY_SCOPE_AGENT);
;                     }
	v_mul_f32_e32 v163, 0.5, v163
	v_mul_f32_e32 v164, 0.5, v164
	v_mul_f32_e32 v165, 0.5, v165
	v_mul_f32_e32 v166, 0.5, v166
	s_mov_b32 vcc_lo, 0x55555555
	s_mov_b32 vcc_hi, 0x55555555
	v_cndmask_b32_e32 v172, v124, v125, vcc
	v_cndmask_b32_e32 v173, v126, v127, vcc
	s_nop 0
	v_cndmask_b32_dpp v124, v172, v124, vcc quad_perm:[1,0,3,2] row_mask:0xf bank_mask:0xf
	v_cndmask_b32_dpp v126, v173, v126, vcc quad_perm:[1,0,3,2] row_mask:0xf bank_mask:0xf
	s_mov_b32 vcc_lo, 0xaaaaaaaa
	s_mov_b32 vcc_hi, 0xaaaaaaaa
	v_cndmask_b32_dpp v125, v172, v125, vcc quad_perm:[1,0,3,2] row_mask:0xf bank_mask:0xf
	v_cndmask_b32_dpp v127, v173, v127, vcc quad_perm:[1,0,3,2] row_mask:0xf bank_mask:0xf
	s_mov_b32 vcc_lo, 0x33333333
	s_mov_b32 vcc_hi, 0x33333333
	v_cndmask_b32_e32 v172, v124, v126, vcc
	v_cndmask_b32_e32 v173, v125, v127, vcc
	s_nop 0
	v_cndmask_b32_dpp v124, v172, v124, vcc quad_perm:[2,3,0,1] row_mask:0xf bank_mask:0xf
	v_cndmask_b32_dpp v125, v173, v125, vcc quad_perm:[2,3,0,1] row_mask:0xf bank_mask:0xf
	s_mov_b32 vcc_lo, 0xcccccccc
	s_mov_b32 vcc_hi, 0xcccccccc
	v_cndmask_b32_dpp v126, v172, v126, vcc quad_perm:[2,3,0,1] row_mask:0xf bank_mask:0xf
	v_cndmask_b32_dpp v127, v173, v127, vcc quad_perm:[2,3,0,1] row_mask:0xf bank_mask:0xf
	v_mul_f32_e32 v124, v124, v163
	v_mul_f32_e32 v125, v125, v163
	v_mul_f32_e32 v126, v126, v163
	v_mul_f32_e32 v127, v127, v163
	global_atomic_add_f32 v[152:153], v124, off offset:-4096
	global_atomic_add_f32 v[152:153], v125, off
	v_lshl_add_u64 v[152:153], v[152:153], 0, s[98:99]
	global_atomic_add_f32 v[152:153], v126, off offset:-4096
	global_atomic_add_f32 v[152:153], v127, off
	s_mov_b32 vcc_lo, 0x55555555
	s_mov_b32 vcc_hi, 0x55555555
	v_cndmask_b32_e32 v172, v120, v121, vcc
	v_cndmask_b32_e32 v173, v122, v123, vcc
	s_nop 0
	v_cndmask_b32_dpp v120, v172, v120, vcc quad_perm:[1,0,3,2] row_mask:0xf bank_mask:0xf
	v_cndmask_b32_dpp v122, v173, v122, vcc quad_perm:[1,0,3,2] row_mask:0xf bank_mask:0xf
	s_mov_b32 vcc_lo, 0xaaaaaaaa
	s_mov_b32 vcc_hi, 0xaaaaaaaa
	v_cndmask_b32_dpp v121, v172, v121, vcc quad_perm:[1,0,3,2] row_mask:0xf bank_mask:0xf
	v_cndmask_b32_dpp v123, v173, v123, vcc quad_perm:[1,0,3,2] row_mask:0xf bank_mask:0xf
	s_mov_b32 vcc_lo, 0x33333333
	s_mov_b32 vcc_hi, 0x33333333
	v_cndmask_b32_e32 v172, v120, v122, vcc
	v_cndmask_b32_e32 v173, v121, v123, vcc
	s_nop 0
	v_cndmask_b32_dpp v120, v172, v120, vcc quad_perm:[2,3,0,1] row_mask:0xf bank_mask:0xf
	v_cndmask_b32_dpp v121, v173, v121, vcc quad_perm:[2,3,0,1] row_mask:0xf bank_mask:0xf
	s_mov_b32 vcc_lo, 0xcccccccc
	s_mov_b32 vcc_hi, 0xcccccccc
	v_cndmask_b32_dpp v122, v172, v122, vcc quad_perm:[2,3,0,1] row_mask:0xf bank_mask:0xf
	v_cndmask_b32_dpp v123, v173, v123, vcc quad_perm:[2,3,0,1] row_mask:0xf bank_mask:0xf
	v_mul_f32_e32 v120, v120, v163
	v_mul_f32_e32 v121, v121, v163
	v_mul_f32_e32 v122, v122, v163
	v_mul_f32_e32 v123, v123, v163
	global_atomic_add_f32 v[150:151], v120, off offset:-4096
	global_atomic_add_f32 v[150:151], v121, off
	v_lshl_add_u64 v[150:151], v[150:151], 0, s[98:99]
	global_atomic_add_f32 v[150:151], v122, off offset:-4096
	global_atomic_add_f32 v[150:151], v123, off
	s_mov_b32 vcc_lo, 0x55555555
	s_mov_b32 vcc_hi, 0x55555555
	v_cndmask_b32_e32 v172, v116, v117, vcc
	v_cndmask_b32_e32 v173, v118, v119, vcc
	s_nop 0
	v_cndmask_b32_dpp v116, v172, v116, vcc quad_perm:[1,0,3,2] row_mask:0xf bank_mask:0xf
	v_cndmask_b32_dpp v118, v173, v118, vcc quad_perm:[1,0,3,2] row_mask:0xf bank_mask:0xf
	s_mov_b32 vcc_lo, 0xaaaaaaaa
	s_mov_b32 vcc_hi, 0xaaaaaaaa
	v_cndmask_b32_dpp v117, v172, v117, vcc quad_perm:[1,0,3,2] row_mask:0xf bank_mask:0xf
	v_cndmask_b32_dpp v119, v173, v119, vcc quad_perm:[1,0,3,2] row_mask:0xf bank_mask:0xf
	s_mov_b32 vcc_lo, 0x33333333
	s_mov_b32 vcc_hi, 0x33333333
	v_cndmask_b32_e32 v172, v116, v118, vcc
	v_cndmask_b32_e32 v173, v117, v119, vcc
	s_nop 0
	v_cndmask_b32_dpp v116, v172, v116, vcc quad_perm:[2,3,0,1] row_mask:0xf bank_mask:0xf
	v_cndmask_b32_dpp v117, v173, v117, vcc quad_perm:[2,3,0,1] row_mask:0xf bank_mask:0xf
	s_mov_b32 vcc_lo, 0xcccccccc
	s_mov_b32 vcc_hi, 0xcccccccc
	v_cndmask_b32_dpp v118, v172, v118, vcc quad_perm:[2,3,0,1] row_mask:0xf bank_mask:0xf
	v_cndmask_b32_dpp v119, v173, v119, vcc quad_perm:[2,3,0,1] row_mask:0xf bank_mask:0xf
	v_mul_f32_e32 v116, v116, v163
	v_mul_f32_e32 v117, v117, v163
	v_mul_f32_e32 v118, v118, v163
	v_mul_f32_e32 v119, v119, v163
	global_atomic_add_f32 v[148:149], v116, off offset:-4096
	global_atomic_add_f32 v[148:149], v117, off
	v_lshl_add_u64 v[148:149], v[148:149], 0, s[98:99]
	global_atomic_add_f32 v[148:149], v118, off offset:-4096
	global_atomic_add_f32 v[148:149], v119, off
	s_mov_b32 vcc_lo, 0x55555555
	s_mov_b32 vcc_hi, 0x55555555
	v_cndmask_b32_e32 v172, v112, v113, vcc
	v_cndmask_b32_e32 v173, v114, v115, vcc
	s_nop 0
	v_cndmask_b32_dpp v112, v172, v112, vcc quad_perm:[1,0,3,2] row_mask:0xf bank_mask:0xf
	v_cndmask_b32_dpp v114, v173, v114, vcc quad_perm:[1,0,3,2] row_mask:0xf bank_mask:0xf
	s_mov_b32 vcc_lo, 0xaaaaaaaa
	s_mov_b32 vcc_hi, 0xaaaaaaaa
	v_cndmask_b32_dpp v113, v172, v113, vcc quad_perm:[1,0,3,2] row_mask:0xf bank_mask:0xf
	v_cndmask_b32_dpp v115, v173, v115, vcc quad_perm:[1,0,3,2] row_mask:0xf bank_mask:0xf
	s_mov_b32 vcc_lo, 0x33333333
	s_mov_b32 vcc_hi, 0x33333333
	v_cndmask_b32_e32 v172, v112, v114, vcc
	v_cndmask_b32_e32 v173, v113, v115, vcc
	s_nop 0
	v_cndmask_b32_dpp v112, v172, v112, vcc quad_perm:[2,3,0,1] row_mask:0xf bank_mask:0xf
	v_cndmask_b32_dpp v113, v173, v113, vcc quad_perm:[2,3,0,1] row_mask:0xf bank_mask:0xf
	s_mov_b32 vcc_lo, 0xcccccccc
	s_mov_b32 vcc_hi, 0xcccccccc
;     __device__ __forceinline__ void operator()(const AccT& acc, const Unit& u, int wr, int wc, int fr, int fq) const {
;     ...
;                 const int n = 256 * u.pn + 128 * bj + 32 * wc + 16 * nn + 4 * fq;
;                 const f32x4 gt = *(const f32x4*)(mod + 4 * 9216 + 2 * 1024 + n) * 0.5f;
;                 float* xb = XR + (size_t)(256 * u.pm + 64 * wr + fr) * 1024 + n;
; #pragma unroll
;                 for (int ai = 0; ai < 2; ++ai)
; #pragma unroll
;                     for (int mm = 0; mm < 4; ++mm) {
;                         float* xp = xb + (size_t)(128 * ai + 16 * mm) * 1024;
;                         const f32x4 v = acc[ai][bj][mm][nn] * gt;
; #pragma unroll
;                         for (int r = 0; r < 4; ++r) (void)__hip_atomic_fetch_add(xp + r, v[r], __ATOMIC_RELAXED, __HIP_MEMORY_SCOPE_AGENT);
;                     }
	v_cndmask_b32_dpp v114, v172, v114, vcc quad_perm:[2,3,0,1] row_mask:0xf bank_mask:0xf
	v_cndmask_b32_dpp v115, v173, v115, vcc quad_perm:[2,3,0,1] row_mask:0xf bank_mask:0xf
	v_mul_f32_e32 v112, v112, v163
	v_mul_f32_e32 v113, v113, v163
	v_mul_f32_e32 v114, v114, v163
	v_mul_f32_e32 v115, v115, v163
	global_atomic_add_f32 v[142:143], v112, off offset:-4096
	global_atomic_add_f32 v[142:143], v113, off
	v_lshl_add_u64 v[142:143], v[142:143], 0, s[98:99]
	global_atomic_add_f32 v[142:143], v114, off offset:-4096
	global_atomic_add_f32 v[142:143], v115, off
	s_mov_b32 vcc_lo, 0x55555555
	s_mov_b32 vcc_hi, 0x55555555
	v_cndmask_b32_e32 v172, v108, v109, vcc
	v_cndmask_b32_e32 v173, v110, v111, vcc
	s_nop 0
	v_cndmask_b32_dpp v108, v172, v108, vcc quad_perm:[1,0,3,2] row_mask:0xf bank_mask:0xf
	v_cndmask_b32_dpp v110, v173, v110, vcc quad_perm:[1,0,3,2] row_mask:0xf bank_mask:0xf
	s_mov_b32 vcc_lo, 0xaaaaaaaa
	s_mov_b32 vcc_hi, 0xaaaaaaaa
	v_cndmask_b32_dpp v109, v172, v109, vcc quad_perm:[1,0,3,2] row_mask:0xf bank_mask:0xf
	v_cndmask_b32_dpp v111, v173, v111, vcc quad_perm:[1,0,3,2] row_mask:0xf bank_mask:0xf
	s_mov_b32 vcc_lo, 0x33333333
	s_mov_b32 vcc_hi, 0x33333333
	v_cndmask_b32_e32 v172, v108, v110, vcc
	v_cndmask_b32_e32 v173, v109, v111, vcc
	s_nop 0
	v_cndmask_b32_dpp v108, v172, v108, vcc quad_perm:[2,3,0,1] row_mask:0xf bank_mask:0xf
	v_cndmask_b32_dpp v109, v173, v109, vcc quad_perm:[2,3,0,1] row_mask:0xf bank_mask:0xf
	s_mov_b32 vcc_lo, 0xcccccccc
	s_mov_b32 vcc_hi, 0xcccccccc
	v_cndmask_b32_dpp v110, v172, v110, vcc quad_perm:[2,3,0,1] row_mask:0xf bank_mask:0xf
	v_cndmask_b32_dpp v111, v173, v111, vcc quad_perm:[2,3,0,1] row_mask:0xf bank_mask:0xf
	v_mul_f32_e32 v108, v108, v163
	v_mul_f32_e32 v109, v109, v163
	v_mul_f32_e32 v110, v110, v163
	v_mul_f32_e32 v111, v111, v163
	global_atomic_add_f32 v[140:141], v108, off offset:-4096
	global_atomic_add_f32 v[140:141], v109, off
	v_lshl_add_u64 v[140:141], v[140:141], 0, s[98:99]
	global_atomic_add_f32 v[140:141], v110, off offset:-4096
	global_atomic_add_f32 v[140:141], v111, off
	s_mov_b32 vcc_lo, 0x55555555
	s_mov_b32 vcc_hi, 0x55555555
	v_cndmask_b32_e32 v172, v104, v105, vcc
	v_cndmask_b32_e32 v173, v106, v107, vcc
	s_nop 0
	v_cndmask_b32_dpp v104, v172, v104, vcc quad_perm:[1,0,3,2] row_mask:0xf bank_mask:0xf
	v_cndmask_b32_dpp v106, v173, v106, vcc quad_perm:[1,0,3,2] row_mask:0xf bank_mask:0xf
	s_mov_b32 vcc_lo, 0xaaaaaaaa
	s_mov_b32 vcc_hi, 0xaaaaaaaa
	v_cndmask_b32_dpp v105, v172, v105, vcc quad_perm:[1,0,3,2] row_mask:0xf bank_mask:0xf
	v_cndmask_b32_dpp v107, v173, v107, vcc quad_perm:[1,0,3,2] row_mask:0xf bank_mask:0xf
	s_mov_b32 vcc_lo, 0x33333333
	s_mov_b32 vcc_hi, 0x33333333
	v_cndmask_b32_e32 v172, v104, v106, vcc
	v_cndmask_b32_e32 v173, v105, v107, vcc
	s_nop 0
	v_cndmask_b32_dpp v104, v172, v104, vcc quad_perm:[2,3,0,1] row_mask:0xf bank_mask:0xf
	v_cndmask_b32_dpp v105, v173, v105, vcc quad_perm:[2,3,0,1] row_mask:0xf bank_mask:0xf
	s_mov_b32 vcc_lo, 0xcccccccc
	s_mov_b32 vcc_hi, 0xcccccccc
	v_cndmask_b32_dpp v106, v172, v106, vcc quad_perm:[2,3,0,1] row_mask:0xf bank_mask:0xf
	v_cndmask_b32_dpp v107, v173, v107, vcc quad_perm:[2,3,0,1] row_mask:0xf bank_mask:0xf
	v_mul_f32_e32 v104, v104, v163
	v_mul_f32_e32 v105, v105, v163
	v_mul_f32_e32 v106, v106, v163
	v_mul_f32_e32 v107, v107, v163
	global_atomic_add_f32 v[138:139], v104, off offset:-4096
	global_atomic_add_f32 v[138:139], v105, off
	v_lshl_add_u64 v[138:139], v[138:139], 0, s[98:99]
	global_atomic_add_f32 v[138:139], v106, off offset:-4096
	global_atomic_add_f32 v[138:139], v107, off
	s_mov_b32 vcc_lo, 0x55555555
	s_mov_b32 vcc_hi, 0x55555555
	v_cndmask_b32_e32 v172, v100, v101, vcc
	v_cndmask_b32_e32 v173, v102, v103, vcc
	s_nop 0
	v_cndmask_b32_dpp v100, v172, v100, vcc quad_perm:[1,0,3,2] row_mask:0xf bank_mask:0xf
	v_cndmask_b32_dpp v102, v173, v102, vcc quad_perm:[1,0,3,2] row_mask:0xf bank_mask:0xf
	s_mov_b32 vcc_lo, 0xaaaaaaaa
	s_mov_b32 vcc_hi, 0xaaaaaaaa
	v_cndmask_b32_dpp v101, v172, v101, vcc quad_perm:[1,0,3,2] row_mask:0xf bank_mask:0xf
	v_cndmask_b32_dpp v103, v173, v103, vcc quad_perm:[1,0,3,2] row_mask:0xf bank_mask:0xf
	s_mov_b32 vcc_lo, 0x33333333
	s_mov_b32 vcc_hi, 0x33333333
	v_cndmask_b32_e32 v172, v100, v102, vcc
	v_cndmask_b32_e32 v173, v101, v103, vcc
	s_nop 0
	v_cndmask_b32_dpp v100, v172, v100, vcc quad_perm:[2,3,0,1] row_mask:0xf bank_mask:0xf
	v_cndmask_b32_dpp v101, v173, v101, vcc quad_perm:[2,3,0,1] row_mask:0xf bank_mask:0xf
	s_mov_b32 vcc_lo, 0xcccccccc
	s_mov_b32 vcc_hi, 0xcccccccc
	v_cndmask_b32_dpp v102, v172, v102, vcc quad_perm:[2,3,0,1] row_mask:0xf bank_mask:0xf
	v_cndmask_b32_dpp v103, v173, v103, vcc quad_perm:[2,3,0,1] row_mask:0xf bank_mask:0xf
	v_mul_f32_e32 v100, v100, v163
	v_mul_f32_e32 v101, v101, v163
	v_mul_f32_e32 v102, v102, v163
	v_mul_f32_e32 v103, v103, v163
	global_atomic_add_f32 v[136:137], v100, off offset:-4096
	global_atomic_add_f32 v[136:137], v101, off
	v_lshl_add_u64 v[136:137], v[136:137], 0, s[98:99]
	global_atomic_add_f32 v[136:137], v102, off offset:-4096
	global_atomic_add_f32 v[136:137], v103, off
	s_mov_b32 vcc_lo, 0x55555555
	s_mov_b32 vcc_hi, 0x55555555
	v_cndmask_b32_e32 v172, v96, v97, vcc
	v_cndmask_b32_e32 v173, v98, v99, vcc
	s_nop 0
	v_cndmask_b32_dpp v96, v172, v96, vcc quad_perm:[1,0,3,2] row_mask:0xf bank_mask:0xf
	v_cndmask_b32_dpp v98, v173, v98, vcc quad_perm:[1,0,3,2] row_mask:0xf bank_mask:0xf
	s_mov_b32 vcc_lo, 0xaaaaaaaa
	s_mov_b32 vcc_hi, 0xaaaaaaaa
	v_cndmask_b32_dpp v97, v172, v97, vcc quad_perm:[1,0,3,2] row_mask:0xf bank_mask:0xf
	v_cndmask_b32_dpp v99, v173, v99, vcc quad_perm:[1,0,3,2] row_mask:0xf bank_mask:0xf
;     __device__ __forceinline__ void operator()(const AccT& acc, const Unit& u, int wr, int wc, int fr, int fq) const {
;     ...
;                 const int n = 256 * u.pn + 128 * bj + 32 * wc + 16 * nn + 4 * fq;
;                 const f32x4 gt = *(const f32x4*)(mod + 4 * 9216 + 2 * 1024 + n) * 0.5f;
;                 float* xb = XR + (size_t)(256 * u.pm + 64 * wr + fr) * 1024 + n;
; #pragma unroll
;                 for (int ai = 0; ai < 2; ++ai)
; #pragma unroll
;                     for (int mm = 0; mm < 4; ++mm) {
;                         float* xp = xb + (size_t)(128 * ai + 16 * mm) * 1024;
;                         const f32x4 v = acc[ai][bj][mm][nn] * gt;
; #pragma unroll
;                         for (int r = 0; r < 4; ++r) (void)__hip_atomic_fetch_add(xp + r, v[r], __ATOMIC_RELAXED, __HIP_MEMORY_SCOPE_AGENT);
;                     }
	s_mov_b32 vcc_lo, 0x33333333
	s_mov_b32 vcc_hi, 0x33333333
	v_cndmask_b32_e32 v172, v96, v98, vcc
	v_cndmask_b32_e32 v173, v97, v99, vcc
	s_nop 0
	v_cndmask_b32_dpp v96, v172, v96, vcc quad_perm:[2,3,0,1] row_mask:0xf bank_mask:0xf
	v_cndmask_b32_dpp v97, v173, v97, vcc quad_perm:[2,3,0,1] row_mask:0xf bank_mask:0xf
	s_mov_b32 vcc_lo, 0xcccccccc
	s_mov_b32 vcc_hi, 0xcccccccc
	v_cndmask_b32_dpp v98, v172, v98, vcc quad_perm:[2,3,0,1] row_mask:0xf bank_mask:0xf
	v_cndmask_b32_dpp v99, v173, v99, vcc quad_perm:[2,3,0,1] row_mask:0xf bank_mask:0xf
	v_mul_f32_e32 v96, v96, v163
	v_mul_f32_e32 v97, v97, v163
	v_mul_f32_e32 v98, v98, v163
	v_mul_f32_e32 v99, v99, v163
	global_atomic_add_f32 v[134:135], v96, off offset:-4096
	global_atomic_add_f32 v[134:135], v97, off
	v_lshl_add_u64 v[134:135], v[134:135], 0, s[98:99]
	global_atomic_add_f32 v[134:135], v98, off offset:-4096
	global_atomic_add_f32 v[134:135], v99, off
	s_mov_b32 vcc_lo, 0x55555555
	s_mov_b32 vcc_hi, 0x55555555
	v_cndmask_b32_e32 v172, v92, v93, vcc
	v_cndmask_b32_e32 v173, v94, v95, vcc
	s_nop 0
	v_cndmask_b32_dpp v92, v172, v92, vcc quad_perm:[1,0,3,2] row_mask:0xf bank_mask:0xf
	v_cndmask_b32_dpp v94, v173, v94, vcc quad_perm:[1,0,3,2] row_mask:0xf bank_mask:0xf
	s_mov_b32 vcc_lo, 0xaaaaaaaa
	s_mov_b32 vcc_hi, 0xaaaaaaaa
	v_cndmask_b32_dpp v93, v172, v93, vcc quad_perm:[1,0,3,2] row_mask:0xf bank_mask:0xf
	v_cndmask_b32_dpp v95, v173, v95, vcc quad_perm:[1,0,3,2] row_mask:0xf bank_mask:0xf
	s_mov_b32 vcc_lo, 0x33333333
	s_mov_b32 vcc_hi, 0x33333333
	v_cndmask_b32_e32 v172, v92, v94, vcc
	v_cndmask_b32_e32 v173, v93, v95, vcc
	s_nop 0
	v_cndmask_b32_dpp v92, v172, v92, vcc quad_perm:[2,3,0,1] row_mask:0xf bank_mask:0xf
	v_cndmask_b32_dpp v93, v173, v93, vcc quad_perm:[2,3,0,1] row_mask:0xf bank_mask:0xf
	s_mov_b32 vcc_lo, 0xcccccccc
	s_mov_b32 vcc_hi, 0xcccccccc
	v_cndmask_b32_dpp v94, v172, v94, vcc quad_perm:[2,3,0,1] row_mask:0xf bank_mask:0xf
	v_cndmask_b32_dpp v95, v173, v95, vcc quad_perm:[2,3,0,1] row_mask:0xf bank_mask:0xf
	v_mul_f32_e32 v92, v92, v164
	v_mul_f32_e32 v93, v93, v164
	v_mul_f32_e32 v94, v94, v164
	v_mul_f32_e32 v95, v95, v164
	global_atomic_add_f32 v[152:153], v94, off offset:-4032
	global_atomic_add_f32 v[152:153], v95, off offset:64
	v_lshl_add_u64 v[152:153], v[152:153], 0, s[100:101]
	global_atomic_add_f32 v[152:153], v92, off offset:-4032
	global_atomic_add_f32 v[152:153], v93, off offset:64
	s_mov_b32 vcc_lo, 0x55555555
	s_mov_b32 vcc_hi, 0x55555555
	v_cndmask_b32_e32 v172, v88, v89, vcc
	v_cndmask_b32_e32 v173, v90, v91, vcc
	s_nop 0
	v_cndmask_b32_dpp v88, v172, v88, vcc quad_perm:[1,0,3,2] row_mask:0xf bank_mask:0xf
	v_cndmask_b32_dpp v90, v173, v90, vcc quad_perm:[1,0,3,2] row_mask:0xf bank_mask:0xf
	s_mov_b32 vcc_lo, 0xaaaaaaaa
	s_mov_b32 vcc_hi, 0xaaaaaaaa
	v_cndmask_b32_dpp v89, v172, v89, vcc quad_perm:[1,0,3,2] row_mask:0xf bank_mask:0xf
	v_cndmask_b32_dpp v91, v173, v91, vcc quad_perm:[1,0,3,2] row_mask:0xf bank_mask:0xf
	s_mov_b32 vcc_lo, 0x33333333
	s_mov_b32 vcc_hi, 0x33333333
	v_cndmask_b32_e32 v172, v88, v90, vcc
	v_cndmask_b32_e32 v173, v89, v91, vcc
	s_nop 0
	v_cndmask_b32_dpp v88, v172, v88, vcc quad_perm:[2,3,0,1] row_mask:0xf bank_mask:0xf
	v_cndmask_b32_dpp v89, v173, v89, vcc quad_perm:[2,3,0,1] row_mask:0xf bank_mask:0xf
	s_mov_b32 vcc_lo, 0xcccccccc
	s_mov_b32 vcc_hi, 0xcccccccc
	v_cndmask_b32_dpp v90, v172, v90, vcc quad_perm:[2,3,0,1] row_mask:0xf bank_mask:0xf
	v_cndmask_b32_dpp v91, v173, v91, vcc quad_perm:[2,3,0,1] row_mask:0xf bank_mask:0xf
	v_mul_f32_e32 v88, v88, v164
	v_mul_f32_e32 v89, v89, v164
	v_mul_f32_e32 v90, v90, v164
	v_mul_f32_e32 v91, v91, v164
	global_atomic_add_f32 v[150:151], v90, off offset:-4032
	global_atomic_add_f32 v[150:151], v91, off offset:64
	v_lshl_add_u64 v[150:151], v[150:151], 0, s[100:101]
	global_atomic_add_f32 v[150:151], v88, off offset:-4032
	global_atomic_add_f32 v[150:151], v89, off offset:64
	s_mov_b32 vcc_lo, 0x55555555
	s_mov_b32 vcc_hi, 0x55555555
	v_cndmask_b32_e32 v172, v84, v85, vcc
	v_cndmask_b32_e32 v173, v86, v87, vcc
	s_nop 0
	v_cndmask_b32_dpp v84, v172, v84, vcc quad_perm:[1,0,3,2] row_mask:0xf bank_mask:0xf
	v_cndmask_b32_dpp v86, v173, v86, vcc quad_perm:[1,0,3,2] row_mask:0xf bank_mask:0xf
	s_mov_b32 vcc_lo, 0xaaaaaaaa
	s_mov_b32 vcc_hi, 0xaaaaaaaa
	v_cndmask_b32_dpp v85, v172, v85, vcc quad_perm:[1,0,3,2] row_mask:0xf bank_mask:0xf
	v_cndmask_b32_dpp v87, v173, v87, vcc quad_perm:[1,0,3,2] row_mask:0xf bank_mask:0xf
	s_mov_b32 vcc_lo, 0x33333333
	s_mov_b32 vcc_hi, 0x33333333
	v_cndmask_b32_e32 v172, v84, v86, vcc
	v_cndmask_b32_e32 v173, v85, v87, vcc
	s_nop 0
	v_cndmask_b32_dpp v84, v172, v84, vcc quad_perm:[2,3,0,1] row_mask:0xf bank_mask:0xf
	v_cndmask_b32_dpp v85, v173, v85, vcc quad_perm:[2,3,0,1] row_mask:0xf bank_mask:0xf
	s_mov_b32 vcc_lo, 0xcccccccc
	s_mov_b32 vcc_hi, 0xcccccccc
	v_cndmask_b32_dpp v86, v172, v86, vcc quad_perm:[2,3,0,1] row_mask:0xf bank_mask:0xf
	v_cndmask_b32_dpp v87, v173, v87, vcc quad_perm:[2,3,0,1] row_mask:0xf bank_mask:0xf
	v_mul_f32_e32 v84, v84, v164
	v_mul_f32_e32 v85, v85, v164
	v_mul_f32_e32 v86, v86, v164
	v_mul_f32_e32 v87, v87, v164
	global_atomic_add_f32 v[148:149], v86, off offset:-4032
	global_atomic_add_f32 v[148:149], v87, off offset:64
	v_lshl_add_u64 v[148:149], v[148:149], 0, s[100:101]
	global_atomic_add_f32 v[148:149], v84, off offset:-4032
	global_atomic_add_f32 v[148:149], v85, off offset:64
	s_mov_b32 vcc_lo, 0x55555555
	s_mov_b32 vcc_hi, 0x55555555
	v_cndmask_b32_e32 v172, v80, v81, vcc
	v_cndmask_b32_e32 v173, v82, v83, vcc
	s_nop 0
	v_cndmask_b32_dpp v80, v172, v80, vcc quad_perm:[1,0,3,2] row_mask:0xf bank_mask:0xf
;     __device__ __forceinline__ void operator()(const AccT& acc, const Unit& u, int wr, int wc, int fr, int fq) const {
;     ...
;                 const int n = 256 * u.pn + 128 * bj + 32 * wc + 16 * nn + 4 * fq;
;                 const f32x4 gt = *(const f32x4*)(mod + 4 * 9216 + 2 * 1024 + n) * 0.5f;
;                 float* xb = XR + (size_t)(256 * u.pm + 64 * wr + fr) * 1024 + n;
; #pragma unroll
;                 for (int ai = 0; ai < 2; ++ai)
; #pragma unroll
;                     for (int mm = 0; mm < 4; ++mm) {
;                         float* xp = xb + (size_t)(128 * ai + 16 * mm) * 1024;
;                         const f32x4 v = acc[ai][bj][mm][nn] * gt;
; #pragma unroll
;                         for (int r = 0; r < 4; ++r) (void)__hip_atomic_fetch_add(xp + r, v[r], __ATOMIC_RELAXED, __HIP_MEMORY_SCOPE_AGENT);
;                     }
	v_cndmask_b32_dpp v82, v173, v82, vcc quad_perm:[1,0,3,2] row_mask:0xf bank_mask:0xf
	s_mov_b32 vcc_lo, 0xaaaaaaaa
	s_mov_b32 vcc_hi, 0xaaaaaaaa
	v_cndmask_b32_dpp v81, v172, v81, vcc quad_perm:[1,0,3,2] row_mask:0xf bank_mask:0xf
	v_cndmask_b32_dpp v83, v173, v83, vcc quad_perm:[1,0,3,2] row_mask:0xf bank_mask:0xf
	s_mov_b32 vcc_lo, 0x33333333
	s_mov_b32 vcc_hi, 0x33333333
	v_cndmask_b32_e32 v172, v80, v82, vcc
	v_cndmask_b32_e32 v173, v81, v83, vcc
	s_nop 0
	v_cndmask_b32_dpp v80, v172, v80, vcc quad_perm:[2,3,0,1] row_mask:0xf bank_mask:0xf
	v_cndmask_b32_dpp v81, v173, v81, vcc quad_perm:[2,3,0,1] row_mask:0xf bank_mask:0xf
	s_mov_b32 vcc_lo, 0xcccccccc
	s_mov_b32 vcc_hi, 0xcccccccc
	v_cndmask_b32_dpp v82, v172, v82, vcc quad_perm:[2,3,0,1] row_mask:0xf bank_mask:0xf
	v_cndmask_b32_dpp v83, v173, v83, vcc quad_perm:[2,3,0,1] row_mask:0xf bank_mask:0xf
	v_mul_f32_e32 v80, v80, v164
	v_mul_f32_e32 v81, v81, v164
	v_mul_f32_e32 v82, v82, v164
	v_mul_f32_e32 v83, v83, v164
	global_atomic_add_f32 v[142:143], v82, off offset:-4032
	global_atomic_add_f32 v[142:143], v83, off offset:64
	v_lshl_add_u64 v[142:143], v[142:143], 0, s[100:101]
	global_atomic_add_f32 v[142:143], v80, off offset:-4032
	global_atomic_add_f32 v[142:143], v81, off offset:64
	s_mov_b32 vcc_lo, 0x55555555
	s_mov_b32 vcc_hi, 0x55555555
	v_cndmask_b32_e32 v172, v76, v77, vcc
	v_cndmask_b32_e32 v173, v78, v79, vcc
	s_nop 0
	v_cndmask_b32_dpp v76, v172, v76, vcc quad_perm:[1,0,3,2] row_mask:0xf bank_mask:0xf
	v_cndmask_b32_dpp v78, v173, v78, vcc quad_perm:[1,0,3,2] row_mask:0xf bank_mask:0xf
	s_mov_b32 vcc_lo, 0xaaaaaaaa
	s_mov_b32 vcc_hi, 0xaaaaaaaa
	v_cndmask_b32_dpp v77, v172, v77, vcc quad_perm:[1,0,3,2] row_mask:0xf bank_mask:0xf
	v_cndmask_b32_dpp v79, v173, v79, vcc quad_perm:[1,0,3,2] row_mask:0xf bank_mask:0xf
	s_mov_b32 vcc_lo, 0x33333333
	s_mov_b32 vcc_hi, 0x33333333
	v_cndmask_b32_e32 v172, v76, v78, vcc
	v_cndmask_b32_e32 v173, v77, v79, vcc
	s_nop 0
	v_cndmask_b32_dpp v76, v172, v76, vcc quad_perm:[2,3,0,1] row_mask:0xf bank_mask:0xf
	v_cndmask_b32_dpp v77, v173, v77, vcc quad_perm:[2,3,0,1] row_mask:0xf bank_mask:0xf
	s_mov_b32 vcc_lo, 0xcccccccc
	s_mov_b32 vcc_hi, 0xcccccccc
	v_cndmask_b32_dpp v78, v172, v78, vcc quad_perm:[2,3,0,1] row_mask:0xf bank_mask:0xf
	v_cndmask_b32_dpp v79, v173, v79, vcc quad_perm:[2,3,0,1] row_mask:0xf bank_mask:0xf
	v_mul_f32_e32 v76, v76, v164
	v_mul_f32_e32 v77, v77, v164
	v_mul_f32_e32 v78, v78, v164
	v_mul_f32_e32 v79, v79, v164
	global_atomic_add_f32 v[140:141], v78, off offset:-4032
	global_atomic_add_f32 v[140:141], v79, off offset:64
	v_lshl_add_u64 v[140:141], v[140:141], 0, s[100:101]
	global_atomic_add_f32 v[140:141], v76, off offset:-4032
	global_atomic_add_f32 v[140:141], v77, off offset:64
	s_mov_b32 vcc_lo, 0x55555555
	s_mov_b32 vcc_hi, 0x55555555
	v_cndmask_b32_e32 v172, v72, v73, vcc
	v_cndmask_b32_e32 v173, v74, v75, vcc
	s_nop 0
	v_cndmask_b32_dpp v72, v172, v72, vcc quad_perm:[1,0,3,2] row_mask:0xf bank_mask:0xf
	v_cndmask_b32_dpp v74, v173, v74, vcc quad_perm:[1,0,3,2] row_mask:0xf bank_mask:0xf
	s_mov_b32 vcc_lo, 0xaaaaaaaa
	s_mov_b32 vcc_hi, 0xaaaaaaaa
	v_cndmask_b32_dpp v73, v172, v73, vcc quad_perm:[1,0,3,2] row_mask:0xf bank_mask:0xf
	v_cndmask_b32_dpp v75, v173, v75, vcc quad_perm:[1,0,3,2] row_mask:0xf bank_mask:0xf
	s_mov_b32 vcc_lo, 0x33333333
	s_mov_b32 vcc_hi, 0x33333333
	v_cndmask_b32_e32 v172, v72, v74, vcc
	v_cndmask_b32_e32 v173, v73, v75, vcc
	s_nop 0
	v_cndmask_b32_dpp v72, v172, v72, vcc quad_perm:[2,3,0,1] row_mask:0xf bank_mask:0xf
	v_cndmask_b32_dpp v73, v173, v73, vcc quad_perm:[2,3,0,1] row_mask:0xf bank_mask:0xf
	s_mov_b32 vcc_lo, 0xcccccccc
	s_mov_b32 vcc_hi, 0xcccccccc
	v_cndmask_b32_dpp v74, v172, v74, vcc quad_perm:[2,3,0,1] row_mask:0xf bank_mask:0xf
	v_cndmask_b32_dpp v75, v173, v75, vcc quad_perm:[2,3,0,1] row_mask:0xf bank_mask:0xf
	v_mul_f32_e32 v72, v72, v164
	v_mul_f32_e32 v73, v73, v164
	v_mul_f32_e32 v74, v74, v164
	v_mul_f32_e32 v75, v75, v164
	global_atomic_add_f32 v[138:139], v74, off offset:-4032
	global_atomic_add_f32 v[138:139], v75, off offset:64
	v_lshl_add_u64 v[138:139], v[138:139], 0, s[100:101]
	global_atomic_add_f32 v[138:139], v72, off offset:-4032
	global_atomic_add_f32 v[138:139], v73, off offset:64
	s_mov_b32 vcc_lo, 0x55555555
	s_mov_b32 vcc_hi, 0x55555555
	v_cndmask_b32_e32 v172, v68, v69, vcc
	v_cndmask_b32_e32 v173, v70, v71, vcc
	s_nop 0
	v_cndmask_b32_dpp v68, v172, v68, vcc quad_perm:[1,0,3,2] row_mask:0xf bank_mask:0xf
	v_cndmask_b32_dpp v70, v173, v70, vcc quad_perm:[1,0,3,2] row_mask:0xf bank_mask:0xf
	s_mov_b32 vcc_lo, 0xaaaaaaaa
	s_mov_b32 vcc_hi, 0xaaaaaaaa
	v_cndmask_b32_dpp v69, v172, v69, vcc quad_perm:[1,0,3,2] row_mask:0xf bank_mask:0xf
	v_cndmask_b32_dpp v71, v173, v71, vcc quad_perm:[1,0,3,2] row_mask:0xf bank_mask:0xf
	s_mov_b32 vcc_lo, 0x33333333
	s_mov_b32 vcc_hi, 0x33333333
	v_cndmask_b32_e32 v172, v68, v70, vcc
	v_cndmask_b32_e32 v173, v69, v71, vcc
	s_nop 0
	v_cndmask_b32_dpp v68, v172, v68, vcc quad_perm:[2,3,0,1] row_mask:0xf bank_mask:0xf
	v_cndmask_b32_dpp v69, v173, v69, vcc quad_perm:[2,3,0,1] row_mask:0xf bank_mask:0xf
	s_mov_b32 vcc_lo, 0xcccccccc
	s_mov_b32 vcc_hi, 0xcccccccc
	v_cndmask_b32_dpp v70, v172, v70, vcc quad_perm:[2,3,0,1] row_mask:0xf bank_mask:0xf
	v_cndmask_b32_dpp v71, v173, v71, vcc quad_perm:[2,3,0,1] row_mask:0xf bank_mask:0xf
	v_mul_f32_e32 v68, v68, v164
	v_mul_f32_e32 v69, v69, v164
	v_mul_f32_e32 v70, v70, v164
	v_mul_f32_e32 v71, v71, v164
	global_atomic_add_f32 v[136:137], v70, off offset:-4032
	global_atomic_add_f32 v[136:137], v71, off offset:64
	v_lshl_add_u64 v[136:137], v[136:137], 0, s[100:101]
;     __device__ __forceinline__ void operator()(const AccT& acc, const Unit& u, int wr, int wc, int fr, int fq) const {
;     ...
;                 const int n = 256 * u.pn + 128 * bj + 32 * wc + 16 * nn + 4 * fq;
;                 const f32x4 gt = *(const f32x4*)(mod + 4 * 9216 + 2 * 1024 + n) * 0.5f;
;                 float* xb = XR + (size_t)(256 * u.pm + 64 * wr + fr) * 1024 + n;
; #pragma unroll
;                 for (int ai = 0; ai < 2; ++ai)
; #pragma unroll
;                     for (int mm = 0; mm < 4; ++mm) {
;                         float* xp = xb + (size_t)(128 * ai + 16 * mm) * 1024;
;                         const f32x4 v = acc[ai][bj][mm][nn] * gt;
; #pragma unroll
;                         for (int r = 0; r < 4; ++r) (void)__hip_atomic_fetch_add(xp + r, v[r], __ATOMIC_RELAXED, __HIP_MEMORY_SCOPE_AGENT);
;                     }
	global_atomic_add_f32 v[136:137], v68, off offset:-4032
	global_atomic_add_f32 v[136:137], v69, off offset:64
	s_mov_b32 vcc_lo, 0x55555555
	s_mov_b32 vcc_hi, 0x55555555
	v_cndmask_b32_e32 v172, v64, v65, vcc
	v_cndmask_b32_e32 v173, v66, v67, vcc
	s_nop 0
	v_cndmask_b32_dpp v64, v172, v64, vcc quad_perm:[1,0,3,2] row_mask:0xf bank_mask:0xf
	v_cndmask_b32_dpp v66, v173, v66, vcc quad_perm:[1,0,3,2] row_mask:0xf bank_mask:0xf
	s_mov_b32 vcc_lo, 0xaaaaaaaa
	s_mov_b32 vcc_hi, 0xaaaaaaaa
	v_cndmask_b32_dpp v65, v172, v65, vcc quad_perm:[1,0,3,2] row_mask:0xf bank_mask:0xf
	v_cndmask_b32_dpp v67, v173, v67, vcc quad_perm:[1,0,3,2] row_mask:0xf bank_mask:0xf
	s_mov_b32 vcc_lo, 0x33333333
	s_mov_b32 vcc_hi, 0x33333333
	v_cndmask_b32_e32 v172, v64, v66, vcc
	v_cndmask_b32_e32 v173, v65, v67, vcc
	s_nop 0
	v_cndmask_b32_dpp v64, v172, v64, vcc quad_perm:[2,3,0,1] row_mask:0xf bank_mask:0xf
	v_cndmask_b32_dpp v65, v173, v65, vcc quad_perm:[2,3,0,1] row_mask:0xf bank_mask:0xf
	s_mov_b32 vcc_lo, 0xcccccccc
	s_mov_b32 vcc_hi, 0xcccccccc
	v_cndmask_b32_dpp v66, v172, v66, vcc quad_perm:[2,3,0,1] row_mask:0xf bank_mask:0xf
	v_cndmask_b32_dpp v67, v173, v67, vcc quad_perm:[2,3,0,1] row_mask:0xf bank_mask:0xf
	v_mul_f32_e32 v64, v64, v164
	v_mul_f32_e32 v65, v65, v164
	v_mul_f32_e32 v66, v66, v164
	v_mul_f32_e32 v67, v67, v164
	global_atomic_add_f32 v[134:135], v66, off offset:-4032
	global_atomic_add_f32 v[134:135], v67, off offset:64
	v_lshl_add_u64 v[134:135], v[134:135], 0, s[100:101]
	global_atomic_add_f32 v[134:135], v64, off offset:-4032
	global_atomic_add_f32 v[134:135], v65, off offset:64
	s_mov_b32 vcc_lo, 0x55555555
	s_mov_b32 vcc_hi, 0x55555555
	v_cndmask_b32_e32 v172, v60, v61, vcc
	v_cndmask_b32_e32 v173, v62, v63, vcc
	s_nop 0
	v_cndmask_b32_dpp v60, v172, v60, vcc quad_perm:[1,0,3,2] row_mask:0xf bank_mask:0xf
	v_cndmask_b32_dpp v62, v173, v62, vcc quad_perm:[1,0,3,2] row_mask:0xf bank_mask:0xf
	s_mov_b32 vcc_lo, 0xaaaaaaaa
	s_mov_b32 vcc_hi, 0xaaaaaaaa
	v_cndmask_b32_dpp v61, v172, v61, vcc quad_perm:[1,0,3,2] row_mask:0xf bank_mask:0xf
	v_cndmask_b32_dpp v63, v173, v63, vcc quad_perm:[1,0,3,2] row_mask:0xf bank_mask:0xf
	s_mov_b32 vcc_lo, 0x33333333
	s_mov_b32 vcc_hi, 0x33333333
	v_cndmask_b32_e32 v172, v60, v62, vcc
	v_cndmask_b32_e32 v173, v61, v63, vcc
	s_nop 0
	v_cndmask_b32_dpp v60, v172, v60, vcc quad_perm:[2,3,0,1] row_mask:0xf bank_mask:0xf
	v_cndmask_b32_dpp v61, v173, v61, vcc quad_perm:[2,3,0,1] row_mask:0xf bank_mask:0xf
	s_mov_b32 vcc_lo, 0xcccccccc
	s_mov_b32 vcc_hi, 0xcccccccc
	v_cndmask_b32_dpp v62, v172, v62, vcc quad_perm:[2,3,0,1] row_mask:0xf bank_mask:0xf
	v_cndmask_b32_dpp v63, v173, v63, vcc quad_perm:[2,3,0,1] row_mask:0xf bank_mask:0xf
	v_mul_f32_e32 v60, v60, v165
	v_mul_f32_e32 v61, v61, v165
	v_mul_f32_e32 v62, v62, v165
	v_mul_f32_e32 v63, v63, v165
	global_atomic_add_f32 v[152:153], v60, off offset:-3584
	global_atomic_add_f32 v[152:153], v61, off offset:512
	v_lshl_add_u64 v[152:153], v[152:153], 0, s[98:99]
	global_atomic_add_f32 v[152:153], v62, off offset:-3584
	global_atomic_add_f32 v[152:153], v63, off offset:512
	s_mov_b32 vcc_lo, 0x55555555
	s_mov_b32 vcc_hi, 0x55555555
	v_cndmask_b32_e32 v172, v56, v57, vcc
	v_cndmask_b32_e32 v173, v58, v59, vcc
	s_nop 0
	v_cndmask_b32_dpp v56, v172, v56, vcc quad_perm:[1,0,3,2] row_mask:0xf bank_mask:0xf
	v_cndmask_b32_dpp v58, v173, v58, vcc quad_perm:[1,0,3,2] row_mask:0xf bank_mask:0xf
	s_mov_b32 vcc_lo, 0xaaaaaaaa
	s_mov_b32 vcc_hi, 0xaaaaaaaa
	v_cndmask_b32_dpp v57, v172, v57, vcc quad_perm:[1,0,3,2] row_mask:0xf bank_mask:0xf
	v_cndmask_b32_dpp v59, v173, v59, vcc quad_perm:[1,0,3,2] row_mask:0xf bank_mask:0xf
	s_mov_b32 vcc_lo, 0x33333333
	s_mov_b32 vcc_hi, 0x33333333
	v_cndmask_b32_e32 v172, v56, v58, vcc
	v_cndmask_b32_e32 v173, v57, v59, vcc
	s_nop 0
	v_cndmask_b32_dpp v56, v172, v56, vcc quad_perm:[2,3,0,1] row_mask:0xf bank_mask:0xf
	v_cndmask_b32_dpp v57, v173, v57, vcc quad_perm:[2,3,0,1] row_mask:0xf bank_mask:0xf
	s_mov_b32 vcc_lo, 0xcccccccc
	s_mov_b32 vcc_hi, 0xcccccccc
	v_cndmask_b32_dpp v58, v172, v58, vcc quad_perm:[2,3,0,1] row_mask:0xf bank_mask:0xf
	v_cndmask_b32_dpp v59, v173, v59, vcc quad_perm:[2,3,0,1] row_mask:0xf bank_mask:0xf
	v_mul_f32_e32 v56, v56, v165
	v_mul_f32_e32 v57, v57, v165
	v_mul_f32_e32 v58, v58, v165
	v_mul_f32_e32 v59, v59, v165
	global_atomic_add_f32 v[150:151], v56, off offset:-3584
	global_atomic_add_f32 v[150:151], v57, off offset:512
	v_lshl_add_u64 v[150:151], v[150:151], 0, s[98:99]
	global_atomic_add_f32 v[150:151], v58, off offset:-3584
	global_atomic_add_f32 v[150:151], v59, off offset:512
	s_mov_b32 vcc_lo, 0x55555555
	s_mov_b32 vcc_hi, 0x55555555
	v_cndmask_b32_e32 v172, v52, v53, vcc
	v_cndmask_b32_e32 v173, v54, v55, vcc
	s_nop 0
	v_cndmask_b32_dpp v52, v172, v52, vcc quad_perm:[1,0,3,2] row_mask:0xf bank_mask:0xf
	v_cndmask_b32_dpp v54, v173, v54, vcc quad_perm:[1,0,3,2] row_mask:0xf bank_mask:0xf
	s_mov_b32 vcc_lo, 0xaaaaaaaa
	s_mov_b32 vcc_hi, 0xaaaaaaaa
	v_cndmask_b32_dpp v53, v172, v53, vcc quad_perm:[1,0,3,2] row_mask:0xf bank_mask:0xf
	v_cndmask_b32_dpp v55, v173, v55, vcc quad_perm:[1,0,3,2] row_mask:0xf bank_mask:0xf
	s_mov_b32 vcc_lo, 0x33333333
	s_mov_b32 vcc_hi, 0x33333333
	v_cndmask_b32_e32 v172, v52, v54, vcc
	v_cndmask_b32_e32 v173, v53, v55, vcc
	s_nop 0
	v_cndmask_b32_dpp v52, v172, v52, vcc quad_perm:[2,3,0,1] row_mask:0xf bank_mask:0xf
	v_cndmask_b32_dpp v53, v173, v53, vcc quad_perm:[2,3,0,1] row_mask:0xf bank_mask:0xf
	s_mov_b32 vcc_lo, 0xcccccccc
	s_mov_b32 vcc_hi, 0xcccccccc
	v_cndmask_b32_dpp v54, v172, v54, vcc quad_perm:[2,3,0,1] row_mask:0xf bank_mask:0xf
;     __device__ __forceinline__ void operator()(const AccT& acc, const Unit& u, int wr, int wc, int fr, int fq) const {
;     ...
;                 const int n = 256 * u.pn + 128 * bj + 32 * wc + 16 * nn + 4 * fq;
;                 const f32x4 gt = *(const f32x4*)(mod + 4 * 9216 + 2 * 1024 + n) * 0.5f;
;                 float* xb = XR + (size_t)(256 * u.pm + 64 * wr + fr) * 1024 + n;
; #pragma unroll
;                 for (int ai = 0; ai < 2; ++ai)
; #pragma unroll
;                     for (int mm = 0; mm < 4; ++mm) {
;                         float* xp = xb + (size_t)(128 * ai + 16 * mm) * 1024;
;                         const f32x4 v = acc[ai][bj][mm][nn] * gt;
; #pragma unroll
;                         for (int r = 0; r < 4; ++r) (void)__hip_atomic_fetch_add(xp + r, v[r], __ATOMIC_RELAXED, __HIP_MEMORY_SCOPE_AGENT);
;                     }
	v_cndmask_b32_dpp v55, v173, v55, vcc quad_perm:[2,3,0,1] row_mask:0xf bank_mask:0xf
	v_mul_f32_e32 v52, v52, v165
	v_mul_f32_e32 v53, v53, v165
	v_mul_f32_e32 v54, v54, v165
	v_mul_f32_e32 v55, v55, v165
	global_atomic_add_f32 v[148:149], v52, off offset:-3584
	global_atomic_add_f32 v[148:149], v53, off offset:512
	v_lshl_add_u64 v[148:149], v[148:149], 0, s[98:99]
	global_atomic_add_f32 v[148:149], v54, off offset:-3584
	global_atomic_add_f32 v[148:149], v55, off offset:512
	s_mov_b32 vcc_lo, 0x55555555
	s_mov_b32 vcc_hi, 0x55555555
	v_cndmask_b32_e32 v172, v48, v49, vcc
	v_cndmask_b32_e32 v173, v50, v51, vcc
	s_nop 0
	v_cndmask_b32_dpp v48, v172, v48, vcc quad_perm:[1,0,3,2] row_mask:0xf bank_mask:0xf
	v_cndmask_b32_dpp v50, v173, v50, vcc quad_perm:[1,0,3,2] row_mask:0xf bank_mask:0xf
	s_mov_b32 vcc_lo, 0xaaaaaaaa
	s_mov_b32 vcc_hi, 0xaaaaaaaa
	v_cndmask_b32_dpp v49, v172, v49, vcc quad_perm:[1,0,3,2] row_mask:0xf bank_mask:0xf
	v_cndmask_b32_dpp v51, v173, v51, vcc quad_perm:[1,0,3,2] row_mask:0xf bank_mask:0xf
	s_mov_b32 vcc_lo, 0x33333333
	s_mov_b32 vcc_hi, 0x33333333
	v_cndmask_b32_e32 v172, v48, v50, vcc
	v_cndmask_b32_e32 v173, v49, v51, vcc
	s_nop 0
	v_cndmask_b32_dpp v48, v172, v48, vcc quad_perm:[2,3,0,1] row_mask:0xf bank_mask:0xf
	v_cndmask_b32_dpp v49, v173, v49, vcc quad_perm:[2,3,0,1] row_mask:0xf bank_mask:0xf
	s_mov_b32 vcc_lo, 0xcccccccc
	s_mov_b32 vcc_hi, 0xcccccccc
	v_cndmask_b32_dpp v50, v172, v50, vcc quad_perm:[2,3,0,1] row_mask:0xf bank_mask:0xf
	v_cndmask_b32_dpp v51, v173, v51, vcc quad_perm:[2,3,0,1] row_mask:0xf bank_mask:0xf
	v_mul_f32_e32 v48, v48, v165
	v_mul_f32_e32 v49, v49, v165
	v_mul_f32_e32 v50, v50, v165
	v_mul_f32_e32 v51, v51, v165
	global_atomic_add_f32 v[142:143], v48, off offset:-3584
	global_atomic_add_f32 v[142:143], v49, off offset:512
	v_lshl_add_u64 v[142:143], v[142:143], 0, s[98:99]
	global_atomic_add_f32 v[142:143], v50, off offset:-3584
	global_atomic_add_f32 v[142:143], v51, off offset:512
	s_mov_b32 vcc_lo, 0x55555555
	s_mov_b32 vcc_hi, 0x55555555
	v_cndmask_b32_e32 v172, v44, v45, vcc
	v_cndmask_b32_e32 v173, v46, v47, vcc
	s_nop 0
	v_cndmask_b32_dpp v44, v172, v44, vcc quad_perm:[1,0,3,2] row_mask:0xf bank_mask:0xf
	v_cndmask_b32_dpp v46, v173, v46, vcc quad_perm:[1,0,3,2] row_mask:0xf bank_mask:0xf
	s_mov_b32 vcc_lo, 0xaaaaaaaa
	s_mov_b32 vcc_hi, 0xaaaaaaaa
	v_cndmask_b32_dpp v45, v172, v45, vcc quad_perm:[1,0,3,2] row_mask:0xf bank_mask:0xf
	v_cndmask_b32_dpp v47, v173, v47, vcc quad_perm:[1,0,3,2] row_mask:0xf bank_mask:0xf
	s_mov_b32 vcc_lo, 0x33333333
	s_mov_b32 vcc_hi, 0x33333333
	v_cndmask_b32_e32 v172, v44, v46, vcc
	v_cndmask_b32_e32 v173, v45, v47, vcc
	s_nop 0
	v_cndmask_b32_dpp v44, v172, v44, vcc quad_perm:[2,3,0,1] row_mask:0xf bank_mask:0xf
	v_cndmask_b32_dpp v45, v173, v45, vcc quad_perm:[2,3,0,1] row_mask:0xf bank_mask:0xf
	s_mov_b32 vcc_lo, 0xcccccccc
	s_mov_b32 vcc_hi, 0xcccccccc
	v_cndmask_b32_dpp v46, v172, v46, vcc quad_perm:[2,3,0,1] row_mask:0xf bank_mask:0xf
	v_cndmask_b32_dpp v47, v173, v47, vcc quad_perm:[2,3,0,1] row_mask:0xf bank_mask:0xf
	v_mul_f32_e32 v44, v44, v165
	v_mul_f32_e32 v45, v45, v165
	v_mul_f32_e32 v46, v46, v165
	v_mul_f32_e32 v47, v47, v165
	global_atomic_add_f32 v[140:141], v44, off offset:-3584
	global_atomic_add_f32 v[140:141], v45, off offset:512
	v_lshl_add_u64 v[140:141], v[140:141], 0, s[98:99]
	global_atomic_add_f32 v[140:141], v46, off offset:-3584
	global_atomic_add_f32 v[140:141], v47, off offset:512
	s_mov_b32 vcc_lo, 0x55555555
	s_mov_b32 vcc_hi, 0x55555555
	v_cndmask_b32_e32 v172, v36, v37, vcc
	v_cndmask_b32_e32 v173, v38, v39, vcc
	s_nop 0
	v_cndmask_b32_dpp v36, v172, v36, vcc quad_perm:[1,0,3,2] row_mask:0xf bank_mask:0xf
	v_cndmask_b32_dpp v38, v173, v38, vcc quad_perm:[1,0,3,2] row_mask:0xf bank_mask:0xf
	s_mov_b32 vcc_lo, 0xaaaaaaaa
	s_mov_b32 vcc_hi, 0xaaaaaaaa
	v_cndmask_b32_dpp v37, v172, v37, vcc quad_perm:[1,0,3,2] row_mask:0xf bank_mask:0xf
	v_cndmask_b32_dpp v39, v173, v39, vcc quad_perm:[1,0,3,2] row_mask:0xf bank_mask:0xf
	s_mov_b32 vcc_lo, 0x33333333
	s_mov_b32 vcc_hi, 0x33333333
	v_cndmask_b32_e32 v172, v36, v38, vcc
	v_cndmask_b32_e32 v173, v37, v39, vcc
	s_nop 0
	v_cndmask_b32_dpp v36, v172, v36, vcc quad_perm:[2,3,0,1] row_mask:0xf bank_mask:0xf
	v_cndmask_b32_dpp v37, v173, v37, vcc quad_perm:[2,3,0,1] row_mask:0xf bank_mask:0xf
	s_mov_b32 vcc_lo, 0xcccccccc
	s_mov_b32 vcc_hi, 0xcccccccc
	v_cndmask_b32_dpp v38, v172, v38, vcc quad_perm:[2,3,0,1] row_mask:0xf bank_mask:0xf
	v_cndmask_b32_dpp v39, v173, v39, vcc quad_perm:[2,3,0,1] row_mask:0xf bank_mask:0xf
	v_mul_f32_e32 v36, v36, v165
	v_mul_f32_e32 v37, v37, v165
	v_mul_f32_e32 v38, v38, v165
	v_mul_f32_e32 v39, v39, v165
	global_atomic_add_f32 v[138:139], v36, off offset:-3584
	global_atomic_add_f32 v[138:139], v37, off offset:512
	v_lshl_add_u64 v[138:139], v[138:139], 0, s[98:99]
	global_atomic_add_f32 v[138:139], v38, off offset:-3584
	global_atomic_add_f32 v[138:139], v39, off offset:512
	s_mov_b32 vcc_lo, 0x55555555
	s_mov_b32 vcc_hi, 0x55555555
	v_cndmask_b32_e32 v172, v28, v29, vcc
	v_cndmask_b32_e32 v173, v30, v31, vcc
	s_nop 0
	v_cndmask_b32_dpp v28, v172, v28, vcc quad_perm:[1,0,3,2] row_mask:0xf bank_mask:0xf
	v_cndmask_b32_dpp v30, v173, v30, vcc quad_perm:[1,0,3,2] row_mask:0xf bank_mask:0xf
	s_mov_b32 vcc_lo, 0xaaaaaaaa
	s_mov_b32 vcc_hi, 0xaaaaaaaa
	v_cndmask_b32_dpp v29, v172, v29, vcc quad_perm:[1,0,3,2] row_mask:0xf bank_mask:0xf
	v_cndmask_b32_dpp v31, v173, v31, vcc quad_perm:[1,0,3,2] row_mask:0xf bank_mask:0xf
	s_mov_b32 vcc_lo, 0x33333333
	s_mov_b32 vcc_hi, 0x33333333
	v_cndmask_b32_e32 v172, v28, v30, vcc
;     __device__ __forceinline__ void operator()(const AccT& acc, const Unit& u, int wr, int wc, int fr, int fq) const {
;     ...
;                 const int n = 256 * u.pn + 128 * bj + 32 * wc + 16 * nn + 4 * fq;
;                 const f32x4 gt = *(const f32x4*)(mod + 4 * 9216 + 2 * 1024 + n) * 0.5f;
;                 float* xb = XR + (size_t)(256 * u.pm + 64 * wr + fr) * 1024 + n;
; #pragma unroll
;                 for (int ai = 0; ai < 2; ++ai)
; #pragma unroll
;                     for (int mm = 0; mm < 4; ++mm) {
;                         float* xp = xb + (size_t)(128 * ai + 16 * mm) * 1024;
;                         const f32x4 v = acc[ai][bj][mm][nn] * gt;
; #pragma unroll
;                         for (int r = 0; r < 4; ++r) (void)__hip_atomic_fetch_add(xp + r, v[r], __ATOMIC_RELAXED, __HIP_MEMORY_SCOPE_AGENT);
;                     }
	v_cndmask_b32_e32 v173, v29, v31, vcc
	s_nop 0
	v_cndmask_b32_dpp v28, v172, v28, vcc quad_perm:[2,3,0,1] row_mask:0xf bank_mask:0xf
	v_cndmask_b32_dpp v29, v173, v29, vcc quad_perm:[2,3,0,1] row_mask:0xf bank_mask:0xf
	s_mov_b32 vcc_lo, 0xcccccccc
	s_mov_b32 vcc_hi, 0xcccccccc
	v_cndmask_b32_dpp v30, v172, v30, vcc quad_perm:[2,3,0,1] row_mask:0xf bank_mask:0xf
	v_cndmask_b32_dpp v31, v173, v31, vcc quad_perm:[2,3,0,1] row_mask:0xf bank_mask:0xf
	v_mul_f32_e32 v28, v28, v165
	v_mul_f32_e32 v29, v29, v165
	v_mul_f32_e32 v30, v30, v165
	v_mul_f32_e32 v31, v31, v165
	global_atomic_add_f32 v[136:137], v28, off offset:-3584
	global_atomic_add_f32 v[136:137], v29, off offset:512
	v_lshl_add_u64 v[136:137], v[136:137], 0, s[98:99]
	global_atomic_add_f32 v[136:137], v30, off offset:-3584
	global_atomic_add_f32 v[136:137], v31, off offset:512
	s_mov_b32 vcc_lo, 0x55555555
	s_mov_b32 vcc_hi, 0x55555555
	v_cndmask_b32_e32 v172, v20, v21, vcc
	v_cndmask_b32_e32 v173, v22, v23, vcc
	s_nop 0
	v_cndmask_b32_dpp v20, v172, v20, vcc quad_perm:[1,0,3,2] row_mask:0xf bank_mask:0xf
	v_cndmask_b32_dpp v22, v173, v22, vcc quad_perm:[1,0,3,2] row_mask:0xf bank_mask:0xf
	s_mov_b32 vcc_lo, 0xaaaaaaaa
	s_mov_b32 vcc_hi, 0xaaaaaaaa
	v_cndmask_b32_dpp v21, v172, v21, vcc quad_perm:[1,0,3,2] row_mask:0xf bank_mask:0xf
	v_cndmask_b32_dpp v23, v173, v23, vcc quad_perm:[1,0,3,2] row_mask:0xf bank_mask:0xf
	s_mov_b32 vcc_lo, 0x33333333
	s_mov_b32 vcc_hi, 0x33333333
	v_cndmask_b32_e32 v172, v20, v22, vcc
	v_cndmask_b32_e32 v173, v21, v23, vcc
	s_nop 0
	v_cndmask_b32_dpp v20, v172, v20, vcc quad_perm:[2,3,0,1] row_mask:0xf bank_mask:0xf
	v_cndmask_b32_dpp v21, v173, v21, vcc quad_perm:[2,3,0,1] row_mask:0xf bank_mask:0xf
	s_mov_b32 vcc_lo, 0xcccccccc
	s_mov_b32 vcc_hi, 0xcccccccc
	v_cndmask_b32_dpp v22, v172, v22, vcc quad_perm:[2,3,0,1] row_mask:0xf bank_mask:0xf
	v_cndmask_b32_dpp v23, v173, v23, vcc quad_perm:[2,3,0,1] row_mask:0xf bank_mask:0xf
	v_mul_f32_e32 v20, v20, v165
	v_mul_f32_e32 v21, v21, v165
	v_mul_f32_e32 v22, v22, v165
	v_mul_f32_e32 v23, v23, v165
	global_atomic_add_f32 v[134:135], v20, off offset:-3584
	global_atomic_add_f32 v[134:135], v21, off offset:512
	v_lshl_add_u64 v[134:135], v[134:135], 0, s[98:99]
	global_atomic_add_f32 v[134:135], v22, off offset:-3584
	global_atomic_add_f32 v[134:135], v23, off offset:512
	s_mov_b32 vcc_lo, 0x55555555
	s_mov_b32 vcc_hi, 0x55555555
	v_cndmask_b32_e32 v172, v40, v41, vcc
	v_cndmask_b32_e32 v173, v42, v43, vcc
	s_nop 0
	v_cndmask_b32_dpp v40, v172, v40, vcc quad_perm:[1,0,3,2] row_mask:0xf bank_mask:0xf
	v_cndmask_b32_dpp v42, v173, v42, vcc quad_perm:[1,0,3,2] row_mask:0xf bank_mask:0xf
	s_mov_b32 vcc_lo, 0xaaaaaaaa
	s_mov_b32 vcc_hi, 0xaaaaaaaa
	v_cndmask_b32_dpp v41, v172, v41, vcc quad_perm:[1,0,3,2] row_mask:0xf bank_mask:0xf
	v_cndmask_b32_dpp v43, v173, v43, vcc quad_perm:[1,0,3,2] row_mask:0xf bank_mask:0xf
	s_mov_b32 vcc_lo, 0x33333333
	s_mov_b32 vcc_hi, 0x33333333
	v_cndmask_b32_e32 v172, v40, v42, vcc
	v_cndmask_b32_e32 v173, v41, v43, vcc
	s_nop 0
	v_cndmask_b32_dpp v40, v172, v40, vcc quad_perm:[2,3,0,1] row_mask:0xf bank_mask:0xf
	v_cndmask_b32_dpp v41, v173, v41, vcc quad_perm:[2,3,0,1] row_mask:0xf bank_mask:0xf
	s_mov_b32 vcc_lo, 0xcccccccc
	s_mov_b32 vcc_hi, 0xcccccccc
	v_cndmask_b32_dpp v42, v172, v42, vcc quad_perm:[2,3,0,1] row_mask:0xf bank_mask:0xf
	v_cndmask_b32_dpp v43, v173, v43, vcc quad_perm:[2,3,0,1] row_mask:0xf bank_mask:0xf
	v_mul_f32_e32 v40, v40, v166
	v_mul_f32_e32 v41, v41, v166
	v_mul_f32_e32 v42, v42, v166
	v_mul_f32_e32 v43, v43, v166
	global_atomic_add_f32 v[152:153], v42, off offset:-3520
	global_atomic_add_f32 v[152:153], v43, off offset:576
	v_lshl_add_u64 v[152:153], v[152:153], 0, s[100:101]
	global_atomic_add_f32 v[152:153], v40, off offset:-3520
	global_atomic_add_f32 v[152:153], v41, off offset:576
	s_mov_b32 vcc_lo, 0x55555555
	s_mov_b32 vcc_hi, 0x55555555
	v_cndmask_b32_e32 v172, v32, v33, vcc
	v_cndmask_b32_e32 v173, v34, v35, vcc
	s_nop 0
	v_cndmask_b32_dpp v32, v172, v32, vcc quad_perm:[1,0,3,2] row_mask:0xf bank_mask:0xf
	v_cndmask_b32_dpp v34, v173, v34, vcc quad_perm:[1,0,3,2] row_mask:0xf bank_mask:0xf
	s_mov_b32 vcc_lo, 0xaaaaaaaa
	s_mov_b32 vcc_hi, 0xaaaaaaaa
	v_cndmask_b32_dpp v33, v172, v33, vcc quad_perm:[1,0,3,2] row_mask:0xf bank_mask:0xf
	v_cndmask_b32_dpp v35, v173, v35, vcc quad_perm:[1,0,3,2] row_mask:0xf bank_mask:0xf
	s_mov_b32 vcc_lo, 0x33333333
	s_mov_b32 vcc_hi, 0x33333333
	v_cndmask_b32_e32 v172, v32, v34, vcc
	v_cndmask_b32_e32 v173, v33, v35, vcc
	s_nop 0
	v_cndmask_b32_dpp v32, v172, v32, vcc quad_perm:[2,3,0,1] row_mask:0xf bank_mask:0xf
	v_cndmask_b32_dpp v33, v173, v33, vcc quad_perm:[2,3,0,1] row_mask:0xf bank_mask:0xf
	s_mov_b32 vcc_lo, 0xcccccccc
	s_mov_b32 vcc_hi, 0xcccccccc
	v_cndmask_b32_dpp v34, v172, v34, vcc quad_perm:[2,3,0,1] row_mask:0xf bank_mask:0xf
	v_cndmask_b32_dpp v35, v173, v35, vcc quad_perm:[2,3,0,1] row_mask:0xf bank_mask:0xf
	v_mul_f32_e32 v32, v32, v166
	v_mul_f32_e32 v33, v33, v166
	v_mul_f32_e32 v34, v34, v166
	v_mul_f32_e32 v35, v35, v166
	global_atomic_add_f32 v[150:151], v34, off offset:-3520
	global_atomic_add_f32 v[150:151], v35, off offset:576
	v_lshl_add_u64 v[150:151], v[150:151], 0, s[100:101]
	global_atomic_add_f32 v[150:151], v32, off offset:-3520
	global_atomic_add_f32 v[150:151], v33, off offset:576
	s_mov_b32 vcc_lo, 0x55555555
	s_mov_b32 vcc_hi, 0x55555555
	v_cndmask_b32_e32 v172, v24, v25, vcc
	v_cndmask_b32_e32 v173, v26, v27, vcc
	s_nop 0
	v_cndmask_b32_dpp v24, v172, v24, vcc quad_perm:[1,0,3,2] row_mask:0xf bank_mask:0xf
	v_cndmask_b32_dpp v26, v173, v26, vcc quad_perm:[1,0,3,2] row_mask:0xf bank_mask:0xf
;     __device__ __forceinline__ void operator()(const AccT& acc, const Unit& u, int wr, int wc, int fr, int fq) const {
;     ...
;                 const int n = 256 * u.pn + 128 * bj + 32 * wc + 16 * nn + 4 * fq;
;                 const f32x4 gt = *(const f32x4*)(mod + 4 * 9216 + 2 * 1024 + n) * 0.5f;
;                 float* xb = XR + (size_t)(256 * u.pm + 64 * wr + fr) * 1024 + n;
; #pragma unroll
;                 for (int ai = 0; ai < 2; ++ai)
; #pragma unroll
;                     for (int mm = 0; mm < 4; ++mm) {
;                         float* xp = xb + (size_t)(128 * ai + 16 * mm) * 1024;
;                         const f32x4 v = acc[ai][bj][mm][nn] * gt;
; #pragma unroll
;                         for (int r = 0; r < 4; ++r) (void)__hip_atomic_fetch_add(xp + r, v[r], __ATOMIC_RELAXED, __HIP_MEMORY_SCOPE_AGENT);
;                     }
	s_mov_b32 vcc_lo, 0xaaaaaaaa
	s_mov_b32 vcc_hi, 0xaaaaaaaa
	v_cndmask_b32_dpp v25, v172, v25, vcc quad_perm:[1,0,3,2] row_mask:0xf bank_mask:0xf
	v_cndmask_b32_dpp v27, v173, v27, vcc quad_perm:[1,0,3,2] row_mask:0xf bank_mask:0xf
	s_mov_b32 vcc_lo, 0x33333333
	s_mov_b32 vcc_hi, 0x33333333
	v_cndmask_b32_e32 v172, v24, v26, vcc
	v_cndmask_b32_e32 v173, v25, v27, vcc
	s_nop 0
	v_cndmask_b32_dpp v24, v172, v24, vcc quad_perm:[2,3,0,1] row_mask:0xf bank_mask:0xf
	v_cndmask_b32_dpp v25, v173, v25, vcc quad_perm:[2,3,0,1] row_mask:0xf bank_mask:0xf
	s_mov_b32 vcc_lo, 0xcccccccc
	s_mov_b32 vcc_hi, 0xcccccccc
	v_cndmask_b32_dpp v26, v172, v26, vcc quad_perm:[2,3,0,1] row_mask:0xf bank_mask:0xf
	v_cndmask_b32_dpp v27, v173, v27, vcc quad_perm:[2,3,0,1] row_mask:0xf bank_mask:0xf
	v_mul_f32_e32 v24, v24, v166
	v_mul_f32_e32 v25, v25, v166
	v_mul_f32_e32 v26, v26, v166
	v_mul_f32_e32 v27, v27, v166
	global_atomic_add_f32 v[148:149], v26, off offset:-3520
	global_atomic_add_f32 v[148:149], v27, off offset:576
	v_lshl_add_u64 v[148:149], v[148:149], 0, s[100:101]
	global_atomic_add_f32 v[148:149], v24, off offset:-3520
	global_atomic_add_f32 v[148:149], v25, off offset:576
	s_mov_b32 vcc_lo, 0x55555555
	s_mov_b32 vcc_hi, 0x55555555
	v_cndmask_b32_e32 v172, v16, v17, vcc
	v_cndmask_b32_e32 v173, v18, v19, vcc
	s_nop 0
	v_cndmask_b32_dpp v16, v172, v16, vcc quad_perm:[1,0,3,2] row_mask:0xf bank_mask:0xf
	v_cndmask_b32_dpp v18, v173, v18, vcc quad_perm:[1,0,3,2] row_mask:0xf bank_mask:0xf
	s_mov_b32 vcc_lo, 0xaaaaaaaa
	s_mov_b32 vcc_hi, 0xaaaaaaaa
	v_cndmask_b32_dpp v17, v172, v17, vcc quad_perm:[1,0,3,2] row_mask:0xf bank_mask:0xf
	v_cndmask_b32_dpp v19, v173, v19, vcc quad_perm:[1,0,3,2] row_mask:0xf bank_mask:0xf
	s_mov_b32 vcc_lo, 0x33333333
	s_mov_b32 vcc_hi, 0x33333333
	v_cndmask_b32_e32 v172, v16, v18, vcc
	v_cndmask_b32_e32 v173, v17, v19, vcc
	s_nop 0
	v_cndmask_b32_dpp v16, v172, v16, vcc quad_perm:[2,3,0,1] row_mask:0xf bank_mask:0xf
	v_cndmask_b32_dpp v17, v173, v17, vcc quad_perm:[2,3,0,1] row_mask:0xf bank_mask:0xf
	s_mov_b32 vcc_lo, 0xcccccccc
	s_mov_b32 vcc_hi, 0xcccccccc
	v_cndmask_b32_dpp v18, v172, v18, vcc quad_perm:[2,3,0,1] row_mask:0xf bank_mask:0xf
	v_cndmask_b32_dpp v19, v173, v19, vcc quad_perm:[2,3,0,1] row_mask:0xf bank_mask:0xf
	v_mul_f32_e32 v16, v16, v166
	v_mul_f32_e32 v17, v17, v166
	v_mul_f32_e32 v18, v18, v166
	v_mul_f32_e32 v19, v19, v166
	global_atomic_add_f32 v[142:143], v18, off offset:-3520
	global_atomic_add_f32 v[142:143], v19, off offset:576
	v_lshl_add_u64 v[142:143], v[142:143], 0, s[100:101]
	global_atomic_add_f32 v[142:143], v16, off offset:-3520
	global_atomic_add_f32 v[142:143], v17, off offset:576
	s_mov_b32 vcc_lo, 0x55555555
	s_mov_b32 vcc_hi, 0x55555555
	v_cndmask_b32_e32 v172, v12, v13, vcc
	v_cndmask_b32_e32 v173, v14, v15, vcc
	s_nop 0
	v_cndmask_b32_dpp v12, v172, v12, vcc quad_perm:[1,0,3,2] row_mask:0xf bank_mask:0xf
	v_cndmask_b32_dpp v14, v173, v14, vcc quad_perm:[1,0,3,2] row_mask:0xf bank_mask:0xf
	s_mov_b32 vcc_lo, 0xaaaaaaaa
	s_mov_b32 vcc_hi, 0xaaaaaaaa
	v_cndmask_b32_dpp v13, v172, v13, vcc quad_perm:[1,0,3,2] row_mask:0xf bank_mask:0xf
	v_cndmask_b32_dpp v15, v173, v15, vcc quad_perm:[1,0,3,2] row_mask:0xf bank_mask:0xf
	s_mov_b32 vcc_lo, 0x33333333
	s_mov_b32 vcc_hi, 0x33333333
	v_cndmask_b32_e32 v172, v12, v14, vcc
	v_cndmask_b32_e32 v173, v13, v15, vcc
	s_nop 0
	v_cndmask_b32_dpp v12, v172, v12, vcc quad_perm:[2,3,0,1] row_mask:0xf bank_mask:0xf
	v_cndmask_b32_dpp v13, v173, v13, vcc quad_perm:[2,3,0,1] row_mask:0xf bank_mask:0xf
	s_mov_b32 vcc_lo, 0xcccccccc
	s_mov_b32 vcc_hi, 0xcccccccc
	v_cndmask_b32_dpp v14, v172, v14, vcc quad_perm:[2,3,0,1] row_mask:0xf bank_mask:0xf
	v_cndmask_b32_dpp v15, v173, v15, vcc quad_perm:[2,3,0,1] row_mask:0xf bank_mask:0xf
	v_mul_f32_e32 v12, v12, v166
	v_mul_f32_e32 v13, v13, v166
	v_mul_f32_e32 v14, v14, v166
	v_mul_f32_e32 v15, v15, v166
	global_atomic_add_f32 v[140:141], v14, off offset:-3520
	global_atomic_add_f32 v[140:141], v15, off offset:576
	v_lshl_add_u64 v[140:141], v[140:141], 0, s[100:101]
	global_atomic_add_f32 v[140:141], v12, off offset:-3520
	global_atomic_add_f32 v[140:141], v13, off offset:576
	s_mov_b32 vcc_lo, 0x55555555
	s_mov_b32 vcc_hi, 0x55555555
	v_cndmask_b32_e32 v172, v8, v9, vcc
	v_cndmask_b32_e32 v173, v10, v11, vcc
	s_nop 0
	v_cndmask_b32_dpp v8, v172, v8, vcc quad_perm:[1,0,3,2] row_mask:0xf bank_mask:0xf
; template <class Epi>
; __device__ __forceinline__ void gemm_phase(PG8_LAS unsigned char* lds, const GemmD g, const Epi& E) {
;     ...
;         if (!has_next) break;
;         if (!midp)
; #pragma unroll
;         for (int a = 0; a < 2; ++a)
; #pragma unroll
;             for (int b = 0; b < 2; ++b)
; #pragma unroll
;                 for (int m = 0; m < 4; ++m)
; #pragma unroll
;                     for (int n = 0; n < 2; ++n) acc[a][b][m][n] = (f32x4){0.f, 0.f, 0.f, 0.f};
;         cur = nxt; cA = nA; cB = nB; ++ui;
;     __device__ __forceinline__ void operator()(const AccT& acc, const Unit& u, int wr, int wc, int fr, int fq) const {
;     ...
;                 const int n = 256 * u.pn + 128 * bj + 32 * wc + 16 * nn + 4 * fq;
;                 const f32x4 gt = *(const f32x4*)(mod + 4 * 9216 + 2 * 1024 + n) * 0.5f;
;                 float* xb = XR + (size_t)(256 * u.pm + 64 * wr + fr) * 1024 + n;
; #pragma unroll
;                 for (int ai = 0; ai < 2; ++ai)
; #pragma unroll
;                     for (int mm = 0; mm < 4; ++mm) {
;                         float* xp = xb + (size_t)(128 * ai + 16 * mm) * 1024;
;                         const f32x4 v = acc[ai][bj][mm][nn] * gt;
; #pragma unroll
;                         for (int r = 0; r < 4; ++r) (void)__hip_atomic_fetch_add(xp + r, v[r], __ATOMIC_RELAXED, __HIP_MEMORY_SCOPE_AGENT);
;                     }
	v_cndmask_b32_dpp v10, v173, v10, vcc quad_perm:[1,0,3,2] row_mask:0xf bank_mask:0xf
	s_mov_b32 vcc_lo, 0xaaaaaaaa
	s_mov_b32 vcc_hi, 0xaaaaaaaa
	v_cndmask_b32_dpp v9, v172, v9, vcc quad_perm:[1,0,3,2] row_mask:0xf bank_mask:0xf
	v_cndmask_b32_dpp v11, v173, v11, vcc quad_perm:[1,0,3,2] row_mask:0xf bank_mask:0xf
	s_mov_b32 vcc_lo, 0x33333333
	s_mov_b32 vcc_hi, 0x33333333
	v_cndmask_b32_e32 v172, v8, v10, vcc
	v_cndmask_b32_e32 v173, v9, v11, vcc
	s_nop 0
	v_cndmask_b32_dpp v8, v172, v8, vcc quad_perm:[2,3,0,1] row_mask:0xf bank_mask:0xf
	v_cndmask_b32_dpp v9, v173, v9, vcc quad_perm:[2,3,0,1] row_mask:0xf bank_mask:0xf
	s_mov_b32 vcc_lo, 0xcccccccc
	s_mov_b32 vcc_hi, 0xcccccccc
	v_cndmask_b32_dpp v10, v172, v10, vcc quad_perm:[2,3,0,1] row_mask:0xf bank_mask:0xf
	v_cndmask_b32_dpp v11, v173, v11, vcc quad_perm:[2,3,0,1] row_mask:0xf bank_mask:0xf
	v_mul_f32_e32 v8, v8, v166
	v_mul_f32_e32 v9, v9, v166
	v_mul_f32_e32 v10, v10, v166
	v_mul_f32_e32 v11, v11, v166
	global_atomic_add_f32 v[138:139], v10, off offset:-3520
	global_atomic_add_f32 v[138:139], v11, off offset:576
	v_lshl_add_u64 v[138:139], v[138:139], 0, s[100:101]
	global_atomic_add_f32 v[138:139], v8, off offset:-3520
	global_atomic_add_f32 v[138:139], v9, off offset:576
	s_mov_b32 vcc_lo, 0x55555555
	s_mov_b32 vcc_hi, 0x55555555
	v_cndmask_b32_e32 v172, v4, v5, vcc
	v_cndmask_b32_e32 v173, v6, v7, vcc
	s_nop 0
	v_cndmask_b32_dpp v4, v172, v4, vcc quad_perm:[1,0,3,2] row_mask:0xf bank_mask:0xf
	v_cndmask_b32_dpp v6, v173, v6, vcc quad_perm:[1,0,3,2] row_mask:0xf bank_mask:0xf
	s_mov_b32 vcc_lo, 0xaaaaaaaa
	s_mov_b32 vcc_hi, 0xaaaaaaaa
	v_cndmask_b32_dpp v5, v172, v5, vcc quad_perm:[1,0,3,2] row_mask:0xf bank_mask:0xf
	v_cndmask_b32_dpp v7, v173, v7, vcc quad_perm:[1,0,3,2] row_mask:0xf bank_mask:0xf
	s_mov_b32 vcc_lo, 0x33333333
	s_mov_b32 vcc_hi, 0x33333333
	v_cndmask_b32_e32 v172, v4, v6, vcc
	v_cndmask_b32_e32 v173, v5, v7, vcc
	s_nop 0
	v_cndmask_b32_dpp v4, v172, v4, vcc quad_perm:[2,3,0,1] row_mask:0xf bank_mask:0xf
	v_cndmask_b32_dpp v5, v173, v5, vcc quad_perm:[2,3,0,1] row_mask:0xf bank_mask:0xf
	s_mov_b32 vcc_lo, 0xcccccccc
	s_mov_b32 vcc_hi, 0xcccccccc
	v_cndmask_b32_dpp v6, v172, v6, vcc quad_perm:[2,3,0,1] row_mask:0xf bank_mask:0xf
	v_cndmask_b32_dpp v7, v173, v7, vcc quad_perm:[2,3,0,1] row_mask:0xf bank_mask:0xf
	v_mul_f32_e32 v4, v4, v166
	v_mul_f32_e32 v5, v5, v166
	v_mul_f32_e32 v6, v6, v166
	v_mul_f32_e32 v7, v7, v166
	global_atomic_add_f32 v[136:137], v6, off offset:-3520
	global_atomic_add_f32 v[136:137], v7, off offset:576
	v_lshl_add_u64 v[136:137], v[136:137], 0, s[100:101]
	global_atomic_add_f32 v[136:137], v4, off offset:-3520
	global_atomic_add_f32 v[136:137], v5, off offset:576
	s_mov_b32 vcc_lo, 0x55555555
	s_mov_b32 vcc_hi, 0x55555555
	v_cndmask_b32_e32 v172, v0, v1, vcc
	v_cndmask_b32_e32 v173, v2, v3, vcc
	s_nop 0
	v_cndmask_b32_dpp v0, v172, v0, vcc quad_perm:[1,0,3,2] row_mask:0xf bank_mask:0xf
	v_cndmask_b32_dpp v2, v173, v2, vcc quad_perm:[1,0,3,2] row_mask:0xf bank_mask:0xf
	s_mov_b32 vcc_lo, 0xaaaaaaaa
	s_mov_b32 vcc_hi, 0xaaaaaaaa
	v_cndmask_b32_dpp v1, v172, v1, vcc quad_perm:[1,0,3,2] row_mask:0xf bank_mask:0xf
	v_cndmask_b32_dpp v3, v173, v3, vcc quad_perm:[1,0,3,2] row_mask:0xf bank_mask:0xf
	s_mov_b32 vcc_lo, 0x33333333
	s_mov_b32 vcc_hi, 0x33333333
	v_cndmask_b32_e32 v172, v0, v2, vcc
	v_cndmask_b32_e32 v173, v1, v3, vcc
	s_nop 0
	v_cndmask_b32_dpp v0, v172, v0, vcc quad_perm:[2,3,0,1] row_mask:0xf bank_mask:0xf
	v_cndmask_b32_dpp v1, v173, v1, vcc quad_perm:[2,3,0,1] row_mask:0xf bank_mask:0xf
	s_mov_b32 vcc_lo, 0xcccccccc
	s_mov_b32 vcc_hi, 0xcccccccc
	v_cndmask_b32_dpp v2, v172, v2, vcc quad_perm:[2,3,0,1] row_mask:0xf bank_mask:0xf
	v_cndmask_b32_dpp v3, v173, v3, vcc quad_perm:[2,3,0,1] row_mask:0xf bank_mask:0xf
	v_mul_f32_e32 v0, v0, v166
	v_mul_f32_e32 v1, v1, v166
	v_mul_f32_e32 v2, v2, v166
	v_mul_f32_e32 v3, v3, v166
	global_atomic_add_f32 v[134:135], v2, off offset:-3520
	global_atomic_add_f32 v[134:135], v3, off offset:576
	v_lshl_add_u64 v[134:135], v[134:135], 0, s[100:101]
	global_atomic_add_f32 v[134:135], v0, off offset:-3520
	global_atomic_add_f32 v[134:135], v1, off offset:576
	s_andn2_b64 vcc, exec, s[2:3]
	s_cbranch_vccnz .LBB0_371
	s_branch .Lctx_pad
	s_nop 0
	s_nop 0
	s_nop 0
	s_nop 0
	s_nop 0
	s_nop 0
	s_nop 0
	s_nop 0
	s_nop 0
	s_nop 0
	s_nop 0
	s_nop 0
	s_nop 0
	s_nop 0
